# p3wt: P3 input-projection epilogue stores write-through (sc1) so the per-unit publish and the phase-end L2 write-back have less to flush
# baseline (speedup 1.0000x reference)
.LBB0_722:
	s_waitcnt lgkmcnt(0)
	v_add_f32_e32 v158, v158, v159
	v_add_f32_e32 v159, v160, v161
	v_add_f32_e32 v154, v154, v155
	v_add_f32_e32 v155, v156, v157
	v_add_f32_e32 v150, v150, v151
	v_add_f32_e32 v151, v152, v153
	v_add_f32_e32 v146, v146, v147
	v_add_f32_e32 v147, v148, v149
	v_add_f32_e32 v142, v142, v143
	v_add_f32_e32 v143, v144, v145
	v_add_f32_e32 v138, v138, v139
	v_add_f32_e32 v139, v140, v141
	v_add_f32_e32 v134, v134, v135
	v_add_f32_e32 v135, v136, v137
	v_add_f32_e32 v130, v130, v131
	v_add_f32_e32 v131, v132, v133
	v_add_f32_e32 v158, v158, v159
	v_add_f32_e32 v154, v154, v155
	v_add_f32_e32 v150, v150, v151
	v_add_f32_e32 v146, v146, v147
	v_add_f32_e32 v142, v142, v143
	v_add_f32_e32 v138, v138, v139
	v_add_f32_e32 v134, v134, v135
	v_add_f32_e32 v130, v130, v131
	v_fmamk_f32 v158, v158, 0x3a800000, v180
	v_fmamk_f32 v154, v154, 0x3a800000, v180
	v_fmamk_f32 v150, v150, 0x3a800000, v180
	v_fmamk_f32 v146, v146, 0x3a800000, v180
	v_fmamk_f32 v142, v142, 0x3a800000, v180
	v_fmamk_f32 v138, v138, 0x3a800000, v180
	v_fmamk_f32 v134, v134, 0x3a800000, v180
	v_fmamk_f32 v130, v130, 0x3a800000, v180
	v_rsq_f32_e32 v158, v158
	v_rsq_f32_e32 v154, v154
	v_rsq_f32_e32 v150, v150
	v_rsq_f32_e32 v146, v146
	v_rsq_f32_e32 v144, v142
	v_rsq_f32_e32 v142, v138
	v_rsq_f32_e32 v140, v134
	v_rsq_f32_e32 v138, v130
	s_cmp_lt_i32 s41, 2
	s_mov_b64 s[46:47], -1
	s_cbranch_scc1 .LBB0_764
	s_cmp_lt_i32 s41, 3
	s_cbranch_scc1 .LBB0_761
	s_cmp_lg_u32 s41, 3
	s_cbranch_scc0 .LBB0_758
	v_add_u32_e32 v139, s16, v183
	s_lshl_b32 s45, s24, 8
	s_lshl_b32 s2, s40, 7
	v_add_u32_e32 v156, s45, v139
	v_mul_f32_e32 v134, v158, v158
	v_pk_mul_f32 v[130:131], v[120:121], v[128:129]
	v_pk_mul_f32 v[136:137], v[118:119], v[126:127]
	s_or_b32 s2, s2, s83
	v_pk_mul_f32 v[132:133], v[130:131], v[134:135] op_sel_hi:[1,0]
	v_pk_mul_f32 v[130:131], v[136:137], v[134:135] op_sel_hi:[1,0]
	v_pk_mul_f32 v[136:137], v[116:117], v[124:125]
	v_pk_mul_f32 v[152:153], v[114:115], v[122:123]
	v_ashrrev_i32_e32 v157, 31, v156
	v_readlane_b32 s12, v255, 0
	v_lshl_add_u32 v148, v182, 3, s2
	v_pk_mul_f32 v[136:137], v[136:137], v[134:135] op_sel_hi:[1,0]
	v_pk_mul_f32 v[134:135], v[152:153], v[134:135] op_sel_hi:[1,0]
	v_lshlrev_b64 v[152:153], 11, v[156:157]
	v_readlane_b32 s13, v255, 1
	v_ashrrev_i32_e32 v149, 31, v148
	s_movk_i32 s2, 0x3fff
	v_lshl_add_u64 v[152:153], s[12:13], 0, v[152:153]
	v_lshl_add_u64 v[152:153], v[148:149], 1, v[152:153]
	v_and_b32_e32 v141, 31, v183
	v_cvt_pk_bf16_f32 v170, v130, v131
	v_cvt_pk_bf16_f32 v171, v132, v133
	v_cvt_pk_bf16_f32 v172, v134, v135
	v_cvt_pk_bf16_f32 v173, v136, v137
	global_store_dwordx4 v[152:153], v[170:173], off sc1
	v_cmp_lt_i32_e32 vcc, s2, v156
	v_subrev_u32_e32 v152, 30, v141
	s_and_saveexec_b64 s[12:13], vcc
	s_xor_b64 s[46:47], exec, s[12:13]
	s_cbranch_execz .LBB0_787
	v_add_u32_e32 v143, 0xffffc000, v156
	v_lshrrev_b32_e32 v160, 5, v143
	v_subrev_u32_e32 v166, 30, v141
	s_or_saveexec_b64 s[46:47], s[46:47]
	v_mov_b64_e32 v[170:171], 0x4428000
	s_xor_b64 exec, exec, s[46:47]
	s_cbranch_execnz .LBB0_788

.LBB0_728:
	v_ashrrev_i32_e32 v161, 31, v160
	v_lshl_add_u64 v[170:171], s[68:69], 0, v[170:171]
	v_lshlrev_b64 v[160:161], 13, v[160:161]
	v_lshl_add_u64 v[160:161], v[170:171], 0, v[160:161]
	v_lshlrev_b64 v[170:171], 12, v[166:167]
	v_lshl_add_u64 v[160:161], v[160:161], 0, v[170:171]
	v_lshl_add_u64 v[160:161], v[148:149], 2, v[160:161]
	global_store_dwordx4 v[160:161], v[130:133], off sc1
	global_store_dwordx4 v[160:161], v[134:137], off offset:16 sc1
.LBB0_729:
	s_or_b64 exec, exec, s[46:47]
	v_add_u32_e32 v143, 16, v139
	v_add_u32_e32 v160, s45, v143
	v_ashrrev_i32_e32 v161, 31, v160
	v_readlane_b32 s12, v255, 0
	v_mul_f32_e32 v134, v154, v154
	v_pk_mul_f32 v[130:131], v[104:105], v[112:113]
	v_pk_mul_f32 v[136:137], v[102:103], v[110:111]
	v_lshlrev_b64 v[184:185], 11, v[160:161]
	v_readlane_b32 s13, v255, 1
	v_pk_mul_f32 v[132:133], v[130:131], v[134:135] op_sel_hi:[1,0]
	v_pk_mul_f32 v[130:131], v[136:137], v[134:135] op_sel_hi:[1,0]
	v_pk_mul_f32 v[136:137], v[100:101], v[108:109]
	v_pk_mul_f32 v[170:171], v[98:99], v[106:107]
	v_lshl_add_u64 v[184:185], s[12:13], 0, v[184:185]
	v_pk_mul_f32 v[136:137], v[136:137], v[134:135] op_sel_hi:[1,0]
	v_pk_mul_f32 v[134:135], v[170:171], v[134:135] op_sel_hi:[1,0]
	v_cvt_pk_bf16_f32 v170, v130, v131
	v_lshl_add_u64 v[184:185], v[148:149], 1, v[184:185]
	v_cmp_lt_i32_e32 vcc, s2, v160
	v_cvt_pk_bf16_f32 v171, v132, v133
	v_cvt_pk_bf16_f32 v172, v134, v135
	v_cvt_pk_bf16_f32 v173, v136, v137
	global_store_dwordx4 v[184:185], v[170:173], off sc1
	s_and_saveexec_b64 s[12:13], vcc
	s_xor_b64 s[46:47], exec, s[12:13]
	s_cbranch_execz .LBB0_789
	v_add_u32_e32 v145, 0xffffc000, v160
	v_and_b32_e32 v143, 31, v143
	v_lshrrev_b32_e32 v170, 5, v145
	v_subrev_u32_e32 v166, 30, v143
	s_or_saveexec_b64 s[46:47], s[46:47]
	v_mov_b64_e32 v[172:173], 0x4428000
	s_xor_b64 exec, exec, s[46:47]
	s_cbranch_execnz .LBB0_790

.LBB0_732:
	v_ashrrev_i32_e32 v171, 31, v170
	v_lshl_add_u64 v[160:161], s[68:69], 0, v[172:173]
	v_lshlrev_b64 v[170:171], 13, v[170:171]
	v_lshl_add_u64 v[160:161], v[160:161], 0, v[170:171]
	v_lshlrev_b64 v[170:171], 12, v[166:167]
	v_lshl_add_u64 v[160:161], v[160:161], 0, v[170:171]
	v_lshl_add_u64 v[160:161], v[148:149], 2, v[160:161]
	global_store_dwordx4 v[160:161], v[130:133], off sc1
	global_store_dwordx4 v[160:161], v[134:137], off offset:16 sc1
.LBB0_733:
	s_or_b64 exec, exec, s[46:47]
	v_add_u32_e32 v160, 32, v156
	v_ashrrev_i32_e32 v161, 31, v160
	v_readlane_b32 s12, v255, 0
	v_mul_f32_e32 v134, v150, v150
	v_pk_mul_f32 v[130:131], v[88:89], v[96:97]
	v_pk_mul_f32 v[136:137], v[86:87], v[94:95]
	v_lshlrev_b64 v[184:185], 11, v[160:161]
	v_readlane_b32 s13, v255, 1
	v_pk_mul_f32 v[132:133], v[130:131], v[134:135] op_sel_hi:[1,0]
	v_pk_mul_f32 v[130:131], v[136:137], v[134:135] op_sel_hi:[1,0]
	v_pk_mul_f32 v[136:137], v[80:81], v[92:93]
	v_pk_mul_f32 v[170:171], v[78:79], v[90:91]
	v_lshl_add_u64 v[184:185], s[12:13], 0, v[184:185]
	v_pk_mul_f32 v[136:137], v[136:137], v[134:135] op_sel_hi:[1,0]
	v_pk_mul_f32 v[134:135], v[170:171], v[134:135] op_sel_hi:[1,0]
	v_cvt_pk_bf16_f32 v170, v130, v131
	v_lshl_add_u64 v[184:185], v[148:149], 1, v[184:185]
	v_cmp_lt_i32_e32 vcc, s2, v160
	v_cvt_pk_bf16_f32 v171, v132, v133
	v_cvt_pk_bf16_f32 v172, v134, v135
	v_cvt_pk_bf16_f32 v173, v136, v137
	global_store_dwordx4 v[184:185], v[170:173], off sc1
	s_and_saveexec_b64 s[12:13], vcc
	s_xor_b64 s[46:47], exec, s[12:13]
	s_cbranch_execz .LBB0_791
	v_add_u32_e32 v143, 0xffffc020, v156
	v_lshrrev_b32_e32 v170, 5, v143
	v_subrev_u32_e32 v166, 30, v141
	s_or_saveexec_b64 s[46:47], s[46:47]
	v_mov_b64_e32 v[172:173], 0x4428000
	s_xor_b64 exec, exec, s[46:47]
	s_cbranch_execnz .LBB0_792

.LBB0_737:
	s_or_b64 exec, exec, s[46:47]
	v_add_u32_e32 v143, 48, v139
	v_add_u32_e32 v160, s45, v143
	v_ashrrev_i32_e32 v161, 31, v160
	v_readlane_b32 s12, v255, 0
	v_mul_f32_e32 v134, v146, v146
	v_pk_mul_f32 v[130:131], v[56:57], v[68:69]
	v_pk_mul_f32 v[136:137], v[54:55], v[66:67]
	v_lshlrev_b64 v[184:185], 11, v[160:161]
	v_readlane_b32 s13, v255, 1
	v_pk_mul_f32 v[132:133], v[130:131], v[134:135] op_sel_hi:[1,0]
	v_pk_mul_f32 v[130:131], v[136:137], v[134:135] op_sel_hi:[1,0]
	v_pk_mul_f32 v[136:137], v[48:49], v[60:61]
	v_pk_mul_f32 v[170:171], v[46:47], v[58:59]
	v_lshl_add_u64 v[184:185], s[12:13], 0, v[184:185]
	v_pk_mul_f32 v[136:137], v[136:137], v[134:135] op_sel_hi:[1,0]
	v_pk_mul_f32 v[134:135], v[170:171], v[134:135] op_sel_hi:[1,0]
	v_cvt_pk_bf16_f32 v170, v130, v131
	v_lshl_add_u64 v[184:185], v[148:149], 1, v[184:185]
	v_cmp_lt_i32_e32 vcc, s2, v160
	v_cvt_pk_bf16_f32 v171, v132, v133
	v_cvt_pk_bf16_f32 v172, v134, v135
	v_cvt_pk_bf16_f32 v173, v136, v137
	global_store_dwordx4 v[184:185], v[170:173], off sc1
	s_and_saveexec_b64 s[12:13], vcc
	s_xor_b64 s[46:47], exec, s[12:13]
	s_cbranch_execz .LBB0_793
	v_add_u32_e32 v145, 0xffffc000, v160
	v_and_b32_e32 v143, 31, v143
	v_lshrrev_b32_e32 v170, 5, v145
	v_subrev_u32_e32 v166, 30, v143
	s_or_saveexec_b64 s[46:47], s[46:47]
	v_mov_b64_e32 v[172:173], 0x4428000
	s_xor_b64 exec, exec, s[46:47]
	s_cbranch_execnz .LBB0_794

.LBB0_741:
	s_or_b64 exec, exec, s[46:47]
	v_add_u32_e32 v160, 0x80, v156
	v_ashrrev_i32_e32 v161, 31, v160
	v_readlane_b32 s12, v255, 0
	v_mul_f32_e32 v134, v144, v144
	v_pk_mul_f32 v[130:131], v[72:73], v[84:85]
	v_pk_mul_f32 v[136:137], v[70:71], v[82:83]
	v_lshlrev_b64 v[184:185], 11, v[160:161]
	v_readlane_b32 s13, v255, 1
	v_pk_mul_f32 v[132:133], v[130:131], v[134:135] op_sel_hi:[1,0]
	v_pk_mul_f32 v[130:131], v[136:137], v[134:135] op_sel_hi:[1,0]
	v_pk_mul_f32 v[136:137], v[64:65], v[76:77]
	v_pk_mul_f32 v[170:171], v[62:63], v[74:75]
	v_lshl_add_u64 v[184:185], s[12:13], 0, v[184:185]
	v_pk_mul_f32 v[136:137], v[136:137], v[134:135] op_sel_hi:[1,0]
	v_pk_mul_f32 v[134:135], v[170:171], v[134:135] op_sel_hi:[1,0]
	v_cvt_pk_bf16_f32 v170, v130, v131
	v_lshl_add_u64 v[184:185], v[148:149], 1, v[184:185]
	v_cmp_lt_i32_e32 vcc, s2, v160
	v_cvt_pk_bf16_f32 v171, v132, v133
	v_cvt_pk_bf16_f32 v172, v134, v135
	v_cvt_pk_bf16_f32 v173, v136, v137
	global_store_dwordx4 v[184:185], v[170:173], off sc1
	s_and_saveexec_b64 s[12:13], vcc
	s_xor_b64 s[46:47], exec, s[12:13]
	s_cbranch_execz .LBB0_795
	v_add_u32_e32 v143, 0xffffc080, v156
	v_lshrrev_b32_e32 v170, 5, v143
	v_subrev_u32_e32 v166, 30, v141
	s_or_saveexec_b64 s[46:47], s[46:47]
	v_mov_b64_e32 v[172:173], 0x4428000
	s_xor_b64 exec, exec, s[46:47]
	s_cbranch_execnz .LBB0_796

.LBB0_745:
	s_or_b64 exec, exec, s[46:47]
	v_add_u32_e32 v141, 0x90, v139
	v_add_u32_e32 v160, s45, v141
	v_ashrrev_i32_e32 v161, 31, v160
	v_readlane_b32 s12, v255, 0
	v_mul_f32_e32 v134, v142, v142
	v_pk_mul_f32 v[130:131], v[40:41], v[52:53]
	v_pk_mul_f32 v[136:137], v[38:39], v[50:51]
	v_lshlrev_b64 v[184:185], 11, v[160:161]
	v_readlane_b32 s13, v255, 1
	v_pk_mul_f32 v[132:133], v[130:131], v[134:135] op_sel_hi:[1,0]
	v_pk_mul_f32 v[130:131], v[136:137], v[134:135] op_sel_hi:[1,0]
	v_pk_mul_f32 v[136:137], v[36:37], v[44:45]
	v_pk_mul_f32 v[170:171], v[34:35], v[42:43]
	v_lshl_add_u64 v[184:185], s[12:13], 0, v[184:185]
	v_pk_mul_f32 v[136:137], v[136:137], v[134:135] op_sel_hi:[1,0]
	v_pk_mul_f32 v[134:135], v[170:171], v[134:135] op_sel_hi:[1,0]
	v_cvt_pk_bf16_f32 v170, v130, v131
	v_lshl_add_u64 v[184:185], v[148:149], 1, v[184:185]
	v_cmp_lt_i32_e32 vcc, s2, v160
	v_cvt_pk_bf16_f32 v171, v132, v133
	v_cvt_pk_bf16_f32 v172, v134, v135
	v_cvt_pk_bf16_f32 v173, v136, v137
	global_store_dwordx4 v[184:185], v[170:173], off sc1
	s_and_saveexec_b64 s[12:13], vcc
	s_xor_b64 s[46:47], exec, s[12:13]
	s_cbranch_execz .LBB0_797
	v_add_u32_e32 v143, 0xffffc000, v160
	v_and_b32_e32 v141, 31, v141
	v_lshrrev_b32_e32 v170, 5, v143
	v_subrev_u32_e32 v166, 30, v141
	s_or_saveexec_b64 s[46:47], s[46:47]
	v_mov_b64_e32 v[172:173], 0x4428000
	s_xor_b64 exec, exec, s[46:47]
	s_cbranch_execnz .LBB0_798

.LBB0_749:
	s_or_b64 exec, exec, s[46:47]
	v_add_u32_e32 v160, 0xa0, v156
	v_ashrrev_i32_e32 v161, 31, v160
	v_readlane_b32 s12, v255, 0
	v_mul_f32_e32 v134, v140, v140
	v_pk_mul_f32 v[130:131], v[24:25], v[32:33]
	v_pk_mul_f32 v[136:137], v[22:23], v[30:31]
	v_lshlrev_b64 v[184:185], 11, v[160:161]
	v_readlane_b32 s13, v255, 1
	v_pk_mul_f32 v[132:133], v[130:131], v[134:135] op_sel_hi:[1,0]
	v_pk_mul_f32 v[130:131], v[136:137], v[134:135] op_sel_hi:[1,0]
	v_pk_mul_f32 v[136:137], v[20:21], v[28:29]
	v_pk_mul_f32 v[170:171], v[18:19], v[26:27]
	v_lshl_add_u64 v[184:185], s[12:13], 0, v[184:185]
	v_pk_mul_f32 v[136:137], v[136:137], v[134:135] op_sel_hi:[1,0]
	v_pk_mul_f32 v[134:135], v[170:171], v[134:135] op_sel_hi:[1,0]
	v_cvt_pk_bf16_f32 v170, v130, v131
	v_lshl_add_u64 v[184:185], v[148:149], 1, v[184:185]
	v_cmp_lt_i32_e32 vcc, s2, v160
	v_cvt_pk_bf16_f32 v171, v132, v133
	v_cvt_pk_bf16_f32 v172, v134, v135
	v_cvt_pk_bf16_f32 v173, v136, v137
	global_store_dwordx4 v[184:185], v[170:173], off sc1
	s_and_saveexec_b64 s[12:13], vcc
	s_xor_b64 s[46:47], exec, s[12:13]
	s_cbranch_execz .LBB0_799
	v_add_u32_e32 v141, 0xffffc0a0, v156
	v_lshrrev_b32_e32 v170, 5, v141
	s_or_saveexec_b64 s[46:47], s[46:47]
	v_mov_b64_e32 v[156:157], 0x4428000
	s_xor_b64 exec, exec, s[46:47]
	s_cbranch_execnz .LBB0_800

.LBB0_752:
	v_ashrrev_i32_e32 v171, 31, v170
	v_lshl_add_u64 v[156:157], s[68:69], 0, v[156:157]
	v_lshlrev_b64 v[160:161], 13, v[170:171]
	v_mov_b32_e32 v153, v167
	v_lshl_add_u64 v[156:157], v[156:157], 0, v[160:161]
	v_lshlrev_b64 v[152:153], 12, v[152:153]
	v_lshl_add_u64 v[152:153], v[156:157], 0, v[152:153]
	v_lshl_add_u64 v[152:153], v[148:149], 2, v[152:153]
	global_store_dwordx4 v[152:153], v[130:133], off sc1
	global_store_dwordx4 v[152:153], v[134:137], off offset:16 sc1
.LBB0_753:
	s_or_b64 exec, exec, s[46:47]
	v_add_u32_e32 v139, 0xb0, v139
	v_add_u32_e32 v152, s45, v139
	v_mul_f32_e32 v134, v138, v138
	v_pk_mul_f32 v[130:131], v[8:9], v[16:17]
	v_pk_mul_f32 v[136:137], v[6:7], v[14:15]
	v_pk_mul_f32 v[132:133], v[130:131], v[134:135] op_sel_hi:[1,0]
	v_pk_mul_f32 v[130:131], v[136:137], v[134:135] op_sel_hi:[1,0]
	v_pk_mul_f32 v[136:137], v[4:5], v[12:13]
	v_pk_mul_f32 v[156:157], v[2:3], v[10:11]
	v_ashrrev_i32_e32 v153, 31, v152
	v_readlane_b32 s12, v255, 0
	v_pk_mul_f32 v[136:137], v[136:137], v[134:135] op_sel_hi:[1,0]
	v_pk_mul_f32 v[134:135], v[156:157], v[134:135] op_sel_hi:[1,0]
	v_lshlrev_b64 v[156:157], 11, v[152:153]
	v_readlane_b32 s13, v255, 1
	v_cmp_lt_i32_e32 vcc, s2, v152
	v_cvt_pk_bf16_f32 v170, v130, v131
	v_cvt_pk_bf16_f32 v171, v132, v133
	v_cvt_pk_bf16_f32 v172, v134, v135
	v_cvt_pk_bf16_f32 v173, v136, v137
	s_nop 0
	v_lshl_add_u64 v[156:157], s[12:13], 0, v[156:157]
	v_lshl_add_u64 v[156:157], v[148:149], 1, v[156:157]
	global_store_dwordx4 v[156:157], v[170:173], off sc1
	s_and_saveexec_b64 s[12:13], vcc
	s_xor_b64 s[46:47], exec, s[12:13]
	s_cbranch_execz .LBB0_801
	v_add_u32_e32 v141, 0xffffc000, v152
	v_and_b32_e32 v139, 31, v139
	v_lshrrev_b32_e32 v156, 5, v141
	v_subrev_u32_e32 v166, 30, v139
	s_or_saveexec_b64 s[46:47], s[46:47]
	v_mov_b64_e32 v[160:161], 0x4428000
	s_xor_b64 exec, exec, s[46:47]
	s_cbranch_execnz .LBB0_802

.LBB0_756:
	v_ashrrev_i32_e32 v157, 31, v156
	v_lshl_add_u64 v[152:153], s[68:69], 0, v[160:161]
	v_lshlrev_b64 v[156:157], 13, v[156:157]
	v_lshl_add_u64 v[152:153], v[152:153], 0, v[156:157]
	v_lshlrev_b64 v[156:157], 12, v[166:167]
	v_lshl_add_u64 v[152:153], v[152:153], 0, v[156:157]
	v_lshl_add_u64 v[148:149], v[148:149], 2, v[152:153]
	global_store_dwordx4 v[148:149], v[130:133], off sc1
	global_store_dwordx4 v[148:149], v[134:137], off offset:16 sc1

.LBB0_758:
	s_and_b64 vcc, exec, s[46:47]
	s_cbranch_vccz .LBB0_760
	s_lshl_b32 s2, s24, 8
	s_add_i32 s2, s2, s16
	v_add_u32_e32 v132, s2, v183
	v_mul_f32_e32 v139, 0xbfb8aa3b, v158
	v_ashrrev_i32_e32 v133, 31, v132
	v_lshlrev_b64 v[134:135], 10, v[132:133]
	v_mul_f32_e32 v133, v118, v139
	v_exp_f32_e32 v133, v133
	v_mul_f32_e32 v136, v114, v139
	v_mul_f32_e32 v137, v119, v139
	v_exp_f32_e32 v136, v136
	v_exp_f32_e32 v137, v137
	v_mul_f32_e32 v141, v115, v139
	v_exp_f32_e32 v141, v141
	v_mul_f32_e32 v143, v120, v139
	v_exp_f32_e32 v143, v143
	v_mul_f32_e32 v145, v116, v139
	v_exp_f32_e32 v145, v145
	v_mul_f32_e32 v147, v121, v139
	v_add_f32_e32 v133, 1.0, v133
	v_exp_f32_e32 v147, v147
	v_mul_f32_e32 v148, v117, v139
	v_rcp_f32_e32 v133, v133
	v_add_f32_e32 v136, 1.0, v136
	v_add_f32_e32 v137, 1.0, v137
	v_exp_f32_e32 v148, v148
	v_rcp_f32_e32 v136, v136
	v_rcp_f32_e32 v137, v137
	v_add_f32_e32 v141, 1.0, v141
	v_rcp_f32_e32 v141, v141
	v_add_f32_e32 v143, 1.0, v143
	v_rcp_f32_e32 v143, v143
	v_add_f32_e32 v145, 1.0, v145
	v_rcp_f32_e32 v145, v145
	v_add_f32_e32 v147, 1.0, v147
	v_fma_f32 v133, v133, s55, 0.5
	s_lshl_b32 s2, s40, 8
	v_rcp_f32_e32 v147, v147
	v_add_f32_e32 v148, 1.0, v148
	v_cvt_pk_u8_f32 v133, v133, 0, 0
	v_fma_f32 v136, v136, s55, 0.5
	v_fma_f32 v137, v137, s55, 0.5
	s_and_b32 s2, s2, 0x300
	v_rcp_f32_e32 v148, v148
	v_cvt_pk_u8_f32 v136, v136, 0, 0
	v_cvt_pk_u8_f32 v133, v137, 1, v133
	v_fma_f32 v137, v141, s55, 0.5
	s_or_b32 s2, s2, s83
	v_cvt_pk_u8_f32 v136, v137, 1, v136
	v_fma_f32 v137, v143, s55, 0.5
	v_readlane_b32 s12, v255, 29
	s_cmp_lt_i32 s40, 20
	v_cvt_pk_u8_f32 v133, v137, 2, v133
	v_fma_f32 v137, v145, s55, 0.5
	v_readlane_b32 s13, v255, 30
	v_lshl_add_u32 v130, v182, 3, s2
	v_cvt_pk_u8_f32 v137, v137, 2, v136
	v_fma_f32 v136, v147, s55, 0.5
	s_cselect_b32 vcc_hi, s13, s43
	s_cselect_b32 vcc_lo, s12, s42
	v_ashrrev_i32_e32 v131, 31, v130
	v_cvt_pk_u8_f32 v136, v136, 3, v133
	v_fma_f32 v133, v148, s55, 0.5
	v_lshl_add_u64 v[134:135], vcc, 0, v[134:135]
	v_cvt_pk_u8_f32 v137, v133, 3, v137
	v_lshl_add_u64 v[134:135], v[134:135], 0, v[130:131]
	v_mul_f32_e32 v133, v126, v139
	global_store_dwordx2 v[134:135], v[136:137], off sc1
	v_exp_f32_e32 v133, v133
	v_mul_f32_e32 v136, v122, v139
	v_mul_f32_e32 v137, v127, v139
	v_exp_f32_e32 v136, v136
	v_exp_f32_e32 v137, v137
	v_mul_f32_e32 v141, v123, v139
	v_exp_f32_e32 v141, v141
	v_mul_f32_e32 v143, v128, v139
	v_exp_f32_e32 v143, v143
	v_mul_f32_e32 v145, v124, v139
	v_exp_f32_e32 v145, v145
	v_mul_f32_e32 v147, v129, v139
	v_add_f32_e32 v133, 1.0, v133
	v_exp_f32_e32 v147, v147
	v_mul_f32_e32 v139, v125, v139
	v_rcp_f32_e32 v133, v133
	v_add_f32_e32 v136, 1.0, v136
	v_add_f32_e32 v137, 1.0, v137
	v_exp_f32_e32 v139, v139
	v_rcp_f32_e32 v136, v136
	v_rcp_f32_e32 v137, v137
	v_add_f32_e32 v141, 1.0, v141
	v_rcp_f32_e32 v141, v141
	v_add_f32_e32 v143, 1.0, v143
	v_rcp_f32_e32 v143, v143
	v_add_f32_e32 v145, 1.0, v145
	v_rcp_f32_e32 v145, v145
	v_add_f32_e32 v147, 1.0, v147
	v_fma_f32 v133, v133, s55, 0.5
	v_rcp_f32_e32 v147, v147
	v_add_f32_e32 v139, 1.0, v139
	v_cvt_pk_u8_f32 v133, v133, 0, 0
	v_fma_f32 v136, v136, s55, 0.5
	v_fma_f32 v137, v137, s55, 0.5
	v_rcp_f32_e32 v139, v139
	v_cvt_pk_u8_f32 v136, v136, 0, 0
	v_cvt_pk_u8_f32 v133, v137, 1, v133
	v_fma_f32 v137, v141, s55, 0.5
	v_cvt_pk_u8_f32 v136, v137, 1, v136
	v_fma_f32 v137, v143, s55, 0.5
	v_cvt_pk_u8_f32 v133, v137, 2, v133
	v_fma_f32 v137, v145, s55, 0.5
	v_cvt_pk_u8_f32 v137, v137, 2, v136
	v_fma_f32 v136, v147, s55, 0.5
	v_cvt_pk_u8_f32 v136, v136, 3, v133
	v_fma_f32 v133, v139, s55, 0.5
	v_cvt_pk_u8_f32 v137, v133, 3, v137
	v_mul_f32_e32 v133, 0xbfb8aa3b, v154
	global_store_dwordx2 v[134:135], v[136:137], off offset:128 sc1
	v_mul_f32_e32 v136, v102, v133
	v_exp_f32_e32 v136, v136
	v_mul_f32_e32 v137, v98, v133
	v_mul_f32_e32 v139, v103, v133
	v_exp_f32_e32 v137, v137
	v_exp_f32_e32 v139, v139
	v_mul_f32_e32 v141, v99, v133
	v_exp_f32_e32 v141, v141
	v_mul_f32_e32 v143, v104, v133
	v_exp_f32_e32 v143, v143
	v_mul_f32_e32 v145, v100, v133
	v_exp_f32_e32 v145, v145
	v_mul_f32_e32 v147, v105, v133
	v_add_f32_e32 v136, 1.0, v136
	v_exp_f32_e32 v147, v147
	v_mul_f32_e32 v148, v101, v133
	v_rcp_f32_e32 v136, v136
	v_add_f32_e32 v137, 1.0, v137
	v_add_f32_e32 v139, 1.0, v139
	v_exp_f32_e32 v148, v148
	v_rcp_f32_e32 v137, v137
	v_rcp_f32_e32 v139, v139
	v_add_f32_e32 v141, 1.0, v141
	v_rcp_f32_e32 v141, v141
	v_add_f32_e32 v143, 1.0, v143
	v_rcp_f32_e32 v143, v143
	v_add_f32_e32 v145, 1.0, v145
	v_rcp_f32_e32 v145, v145
	v_add_f32_e32 v147, 1.0, v147
	v_fma_f32 v136, v136, s55, 0.5
	v_rcp_f32_e32 v147, v147
	v_add_f32_e32 v148, 1.0, v148
	v_cvt_pk_u8_f32 v136, v136, 0, 0
	v_fma_f32 v137, v137, s55, 0.5
	v_fma_f32 v139, v139, s55, 0.5
	v_rcp_f32_e32 v148, v148
	v_cvt_pk_u8_f32 v137, v137, 0, 0
	v_cvt_pk_u8_f32 v136, v139, 1, v136
	v_fma_f32 v139, v141, s55, 0.5
	v_add_u32_e32 v134, 16, v132
	v_cvt_pk_u8_f32 v137, v139, 1, v137
	v_fma_f32 v139, v143, s55, 0.5
	v_ashrrev_i32_e32 v135, 31, v134
	v_cvt_pk_u8_f32 v136, v139, 2, v136
	v_fma_f32 v139, v145, s55, 0.5
	v_lshlrev_b64 v[134:135], 10, v[134:135]
	v_cvt_pk_u8_f32 v137, v139, 2, v137
	v_fma_f32 v139, v147, s55, 0.5
	v_cvt_pk_u8_f32 v136, v139, 3, v136
	v_fma_f32 v139, v148, s55, 0.5
	v_lshl_add_u64 v[134:135], vcc, 0, v[134:135]
	v_cvt_pk_u8_f32 v137, v139, 3, v137
	v_lshl_add_u64 v[134:135], v[134:135], 0, v[130:131]
	global_store_dwordx2 v[134:135], v[136:137], off sc1
	v_mul_f32_e32 v136, v110, v133
	v_exp_f32_e32 v136, v136
	v_mul_f32_e32 v137, v106, v133
	v_mul_f32_e32 v139, v111, v133
	v_exp_f32_e32 v137, v137
	v_exp_f32_e32 v139, v139
	v_mul_f32_e32 v141, v107, v133
	v_exp_f32_e32 v141, v141
	v_mul_f32_e32 v143, v112, v133
	v_exp_f32_e32 v143, v143
	v_mul_f32_e32 v145, v108, v133
	v_exp_f32_e32 v145, v145
	v_mul_f32_e32 v147, v113, v133
	v_mul_f32_e32 v133, v109, v133
	v_add_f32_e32 v136, 1.0, v136
	v_exp_f32_e32 v147, v147
	v_exp_f32_e32 v133, v133
	v_rcp_f32_e32 v136, v136
	v_add_f32_e32 v137, 1.0, v137
	v_add_f32_e32 v139, 1.0, v139
	v_rcp_f32_e32 v137, v137
	v_rcp_f32_e32 v139, v139
	v_add_f32_e32 v141, 1.0, v141
	v_rcp_f32_e32 v141, v141
	v_add_f32_e32 v143, 1.0, v143
	v_rcp_f32_e32 v143, v143
	v_add_f32_e32 v145, 1.0, v145
	v_rcp_f32_e32 v145, v145
	v_add_f32_e32 v147, 1.0, v147
	v_add_f32_e32 v133, 1.0, v133
	v_fma_f32 v136, v136, s55, 0.5
	v_rcp_f32_e32 v147, v147
	v_rcp_f32_e32 v133, v133
	v_cvt_pk_u8_f32 v136, v136, 0, 0
	v_fma_f32 v137, v137, s55, 0.5
	v_fma_f32 v139, v139, s55, 0.5
	v_cvt_pk_u8_f32 v137, v137, 0, 0
	v_cvt_pk_u8_f32 v136, v139, 1, v136
	v_fma_f32 v139, v141, s55, 0.5
	v_cvt_pk_u8_f32 v137, v139, 1, v137
	v_fma_f32 v139, v143, s55, 0.5
	v_cvt_pk_u8_f32 v136, v139, 2, v136
	v_fma_f32 v139, v145, s55, 0.5
	v_cvt_pk_u8_f32 v137, v139, 2, v137
	v_fma_f32 v139, v147, s55, 0.5
	v_fma_f32 v133, v133, s55, 0.5
	v_cvt_pk_u8_f32 v136, v139, 3, v136
	v_cvt_pk_u8_f32 v137, v133, 3, v137
	v_mul_f32_e32 v133, 0xbfb8aa3b, v150
	global_store_dwordx2 v[134:135], v[136:137], off offset:128 sc1
	v_mul_f32_e32 v136, v86, v133
	v_exp_f32_e32 v136, v136
	v_mul_f32_e32 v137, v78, v133
	v_mul_f32_e32 v139, v87, v133
	v_exp_f32_e32 v137, v137
	v_exp_f32_e32 v139, v139
	v_mul_f32_e32 v141, v79, v133
	v_exp_f32_e32 v141, v141
	v_mul_f32_e32 v143, v88, v133
	v_exp_f32_e32 v143, v143
	v_mul_f32_e32 v145, v80, v133
	v_exp_f32_e32 v145, v145
	v_mul_f32_e32 v147, v89, v133
	v_add_f32_e32 v136, 1.0, v136
	v_exp_f32_e32 v147, v147
	v_mul_f32_e32 v148, v81, v133
	v_rcp_f32_e32 v136, v136
	v_add_f32_e32 v137, 1.0, v137
	v_add_f32_e32 v139, 1.0, v139
	v_exp_f32_e32 v148, v148
	v_rcp_f32_e32 v137, v137
	v_rcp_f32_e32 v139, v139
	v_add_f32_e32 v141, 1.0, v141
	v_rcp_f32_e32 v141, v141
	v_add_f32_e32 v143, 1.0, v143
	v_rcp_f32_e32 v143, v143
	v_add_f32_e32 v145, 1.0, v145
	v_rcp_f32_e32 v145, v145
	v_add_f32_e32 v147, 1.0, v147
	v_fma_f32 v136, v136, s55, 0.5
	v_rcp_f32_e32 v147, v147
	v_add_f32_e32 v148, 1.0, v148
	v_cvt_pk_u8_f32 v136, v136, 0, 0
	v_fma_f32 v137, v137, s55, 0.5
	v_fma_f32 v139, v139, s55, 0.5
	v_rcp_f32_e32 v148, v148
	v_cvt_pk_u8_f32 v137, v137, 0, 0
	v_cvt_pk_u8_f32 v136, v139, 1, v136
	v_fma_f32 v139, v141, s55, 0.5
	v_add_u32_e32 v134, 32, v132
	v_cvt_pk_u8_f32 v137, v139, 1, v137
	v_fma_f32 v139, v143, s55, 0.5
	v_ashrrev_i32_e32 v135, 31, v134
	v_cvt_pk_u8_f32 v136, v139, 2, v136
	v_fma_f32 v139, v145, s55, 0.5
	v_lshlrev_b64 v[134:135], 10, v[134:135]
	v_cvt_pk_u8_f32 v137, v139, 2, v137
	v_fma_f32 v139, v147, s55, 0.5
	v_cvt_pk_u8_f32 v136, v139, 3, v136
	v_fma_f32 v139, v148, s55, 0.5
	v_lshl_add_u64 v[134:135], vcc, 0, v[134:135]
	v_cvt_pk_u8_f32 v137, v139, 3, v137
	v_lshl_add_u64 v[134:135], v[134:135], 0, v[130:131]
	global_store_dwordx2 v[134:135], v[136:137], off sc1
	v_mul_f32_e32 v136, v94, v133
	v_exp_f32_e32 v136, v136
	v_mul_f32_e32 v137, v90, v133
	v_mul_f32_e32 v139, v95, v133
	v_exp_f32_e32 v137, v137
	v_exp_f32_e32 v139, v139
	v_mul_f32_e32 v141, v91, v133
	v_exp_f32_e32 v141, v141
	v_mul_f32_e32 v143, v96, v133
	v_exp_f32_e32 v143, v143
	v_mul_f32_e32 v145, v92, v133
	v_exp_f32_e32 v145, v145
	v_mul_f32_e32 v147, v97, v133
	v_mul_f32_e32 v133, v93, v133
	v_add_f32_e32 v136, 1.0, v136
	v_exp_f32_e32 v147, v147
	v_exp_f32_e32 v133, v133
	v_rcp_f32_e32 v136, v136
	v_add_f32_e32 v137, 1.0, v137
	v_add_f32_e32 v139, 1.0, v139
	v_rcp_f32_e32 v137, v137
	v_rcp_f32_e32 v139, v139
	v_add_f32_e32 v141, 1.0, v141
	v_rcp_f32_e32 v141, v141
	v_add_f32_e32 v143, 1.0, v143
	v_rcp_f32_e32 v143, v143
	v_add_f32_e32 v145, 1.0, v145
	v_rcp_f32_e32 v145, v145
	v_add_f32_e32 v147, 1.0, v147
	v_add_f32_e32 v133, 1.0, v133
	v_fma_f32 v136, v136, s55, 0.5
	v_rcp_f32_e32 v147, v147
	v_rcp_f32_e32 v133, v133
	v_cvt_pk_u8_f32 v136, v136, 0, 0
	v_fma_f32 v137, v137, s55, 0.5
	v_fma_f32 v139, v139, s55, 0.5
	v_cvt_pk_u8_f32 v137, v137, 0, 0
	v_cvt_pk_u8_f32 v136, v139, 1, v136
	v_fma_f32 v139, v141, s55, 0.5
	v_cvt_pk_u8_f32 v137, v139, 1, v137
	v_fma_f32 v139, v143, s55, 0.5
	v_cvt_pk_u8_f32 v136, v139, 2, v136
	v_fma_f32 v139, v145, s55, 0.5
	v_cvt_pk_u8_f32 v137, v139, 2, v137
	v_fma_f32 v139, v147, s55, 0.5
	v_fma_f32 v133, v133, s55, 0.5
	v_cvt_pk_u8_f32 v136, v139, 3, v136
	v_cvt_pk_u8_f32 v137, v133, 3, v137
	v_mul_f32_e32 v133, 0xbfb8aa3b, v146
	global_store_dwordx2 v[134:135], v[136:137], off offset:128 sc1
	v_mul_f32_e32 v136, v54, v133
	v_exp_f32_e32 v136, v136
	v_mul_f32_e32 v137, v46, v133
	v_mul_f32_e32 v139, v55, v133
	v_exp_f32_e32 v137, v137
	v_exp_f32_e32 v139, v139
	v_mul_f32_e32 v141, v47, v133
	v_exp_f32_e32 v141, v141
	v_mul_f32_e32 v143, v56, v133
	v_exp_f32_e32 v143, v143
	v_mul_f32_e32 v145, v48, v133
	v_exp_f32_e32 v145, v145
	v_mul_f32_e32 v147, v57, v133
	v_add_f32_e32 v136, 1.0, v136
	v_exp_f32_e32 v147, v147
	v_mul_f32_e32 v148, v49, v133
	v_rcp_f32_e32 v136, v136
	v_add_f32_e32 v137, 1.0, v137
	v_add_f32_e32 v139, 1.0, v139
	v_exp_f32_e32 v148, v148
	v_rcp_f32_e32 v137, v137
	v_rcp_f32_e32 v139, v139
	v_add_f32_e32 v141, 1.0, v141
	v_rcp_f32_e32 v141, v141
	v_add_f32_e32 v143, 1.0, v143
	v_rcp_f32_e32 v143, v143
	v_add_f32_e32 v145, 1.0, v145
	v_rcp_f32_e32 v145, v145
	v_add_f32_e32 v147, 1.0, v147
	v_fma_f32 v136, v136, s55, 0.5
	v_rcp_f32_e32 v147, v147
	v_add_f32_e32 v148, 1.0, v148
	v_cvt_pk_u8_f32 v136, v136, 0, 0
	v_fma_f32 v137, v137, s55, 0.5
	v_fma_f32 v139, v139, s55, 0.5
	v_rcp_f32_e32 v148, v148
	v_cvt_pk_u8_f32 v137, v137, 0, 0
	v_cvt_pk_u8_f32 v136, v139, 1, v136
	v_fma_f32 v139, v141, s55, 0.5
	v_add_u32_e32 v134, 48, v132
	v_cvt_pk_u8_f32 v137, v139, 1, v137
	v_fma_f32 v139, v143, s55, 0.5
	v_ashrrev_i32_e32 v135, 31, v134
	v_cvt_pk_u8_f32 v136, v139, 2, v136
	v_fma_f32 v139, v145, s55, 0.5
	v_lshlrev_b64 v[134:135], 10, v[134:135]
	v_cvt_pk_u8_f32 v137, v139, 2, v137
	v_fma_f32 v139, v147, s55, 0.5
	v_cvt_pk_u8_f32 v136, v139, 3, v136
	v_fma_f32 v139, v148, s55, 0.5
	v_lshl_add_u64 v[134:135], vcc, 0, v[134:135]
	v_cvt_pk_u8_f32 v137, v139, 3, v137
	v_lshl_add_u64 v[134:135], v[134:135], 0, v[130:131]
	global_store_dwordx2 v[134:135], v[136:137], off sc1
	v_mul_f32_e32 v136, v66, v133
	v_exp_f32_e32 v136, v136
	v_mul_f32_e32 v137, v58, v133
	v_mul_f32_e32 v139, v67, v133
	v_exp_f32_e32 v137, v137
	v_exp_f32_e32 v139, v139
	v_mul_f32_e32 v141, v59, v133
	v_exp_f32_e32 v141, v141
	v_mul_f32_e32 v143, v68, v133
	v_exp_f32_e32 v143, v143
	v_mul_f32_e32 v145, v60, v133
	v_exp_f32_e32 v145, v145
	v_mul_f32_e32 v147, v69, v133
	v_mul_f32_e32 v133, v61, v133
	v_add_f32_e32 v136, 1.0, v136
	v_exp_f32_e32 v147, v147
	v_exp_f32_e32 v133, v133
	v_rcp_f32_e32 v136, v136
	v_add_f32_e32 v137, 1.0, v137
	v_add_f32_e32 v139, 1.0, v139
	v_rcp_f32_e32 v137, v137
	v_rcp_f32_e32 v139, v139
	v_add_f32_e32 v141, 1.0, v141
	v_rcp_f32_e32 v141, v141
	v_add_f32_e32 v143, 1.0, v143
	v_rcp_f32_e32 v143, v143
	v_add_f32_e32 v145, 1.0, v145
	v_rcp_f32_e32 v145, v145
	v_add_f32_e32 v147, 1.0, v147
	v_add_f32_e32 v133, 1.0, v133
	v_fma_f32 v136, v136, s55, 0.5
	v_rcp_f32_e32 v147, v147
	v_rcp_f32_e32 v133, v133
	v_cvt_pk_u8_f32 v136, v136, 0, 0
	v_fma_f32 v137, v137, s55, 0.5
	v_fma_f32 v139, v139, s55, 0.5
	v_cvt_pk_u8_f32 v137, v137, 0, 0
	v_cvt_pk_u8_f32 v136, v139, 1, v136
	v_fma_f32 v139, v141, s55, 0.5
	v_cvt_pk_u8_f32 v137, v139, 1, v137
	v_fma_f32 v139, v143, s55, 0.5
	v_cvt_pk_u8_f32 v136, v139, 2, v136
	v_fma_f32 v139, v145, s55, 0.5
	v_cvt_pk_u8_f32 v137, v139, 2, v137
	v_fma_f32 v139, v147, s55, 0.5
	v_fma_f32 v133, v133, s55, 0.5
	v_cvt_pk_u8_f32 v136, v139, 3, v136
	v_cvt_pk_u8_f32 v137, v133, 3, v137
	v_mul_f32_e32 v133, 0xbfb8aa3b, v144
	global_store_dwordx2 v[134:135], v[136:137], off offset:128 sc1
	v_mul_f32_e32 v136, v70, v133
	v_exp_f32_e32 v136, v136
	v_mul_f32_e32 v137, v62, v133
	v_mul_f32_e32 v139, v71, v133
	v_exp_f32_e32 v137, v137
	v_exp_f32_e32 v139, v139
	v_mul_f32_e32 v141, v63, v133
	v_exp_f32_e32 v141, v141
	v_mul_f32_e32 v143, v72, v133
	v_exp_f32_e32 v143, v143
	v_mul_f32_e32 v145, v64, v133
	v_exp_f32_e32 v145, v145
	v_mul_f32_e32 v147, v73, v133
	v_add_f32_e32 v136, 1.0, v136
	v_exp_f32_e32 v147, v147
	v_mul_f32_e32 v148, v65, v133
	v_rcp_f32_e32 v136, v136
	v_add_f32_e32 v137, 1.0, v137
	v_add_f32_e32 v139, 1.0, v139
	v_exp_f32_e32 v148, v148
	v_rcp_f32_e32 v137, v137
	v_rcp_f32_e32 v139, v139
	v_add_f32_e32 v141, 1.0, v141
	v_rcp_f32_e32 v141, v141
	v_add_f32_e32 v143, 1.0, v143
	v_rcp_f32_e32 v143, v143
	v_add_f32_e32 v145, 1.0, v145
	v_rcp_f32_e32 v145, v145
	v_add_f32_e32 v147, 1.0, v147
	v_fma_f32 v136, v136, s55, 0.5
	v_rcp_f32_e32 v147, v147
	v_add_f32_e32 v148, 1.0, v148
	v_cvt_pk_u8_f32 v136, v136, 0, 0
	v_fma_f32 v137, v137, s55, 0.5
	v_fma_f32 v139, v139, s55, 0.5
	v_rcp_f32_e32 v148, v148
	v_cvt_pk_u8_f32 v137, v137, 0, 0
	v_cvt_pk_u8_f32 v136, v139, 1, v136
	v_fma_f32 v139, v141, s55, 0.5
	v_add_u32_e32 v134, 0x80, v132
	v_cvt_pk_u8_f32 v137, v139, 1, v137
	v_fma_f32 v139, v143, s55, 0.5
	v_ashrrev_i32_e32 v135, 31, v134
	v_cvt_pk_u8_f32 v136, v139, 2, v136
	v_fma_f32 v139, v145, s55, 0.5
	v_lshlrev_b64 v[134:135], 10, v[134:135]
	v_cvt_pk_u8_f32 v137, v139, 2, v137
	v_fma_f32 v139, v147, s55, 0.5
	v_cvt_pk_u8_f32 v136, v139, 3, v136
	v_fma_f32 v139, v148, s55, 0.5
	v_lshl_add_u64 v[134:135], vcc, 0, v[134:135]
	v_cvt_pk_u8_f32 v137, v139, 3, v137
	v_lshl_add_u64 v[134:135], v[134:135], 0, v[130:131]
	global_store_dwordx2 v[134:135], v[136:137], off sc1
	v_mul_f32_e32 v136, v82, v133
	v_exp_f32_e32 v136, v136
	v_mul_f32_e32 v137, v74, v133
	v_mul_f32_e32 v139, v83, v133
	v_exp_f32_e32 v137, v137
	v_exp_f32_e32 v139, v139
	v_mul_f32_e32 v141, v75, v133
	v_exp_f32_e32 v141, v141
	v_mul_f32_e32 v143, v84, v133
	v_exp_f32_e32 v143, v143
	v_mul_f32_e32 v145, v76, v133
	v_exp_f32_e32 v145, v145
	v_mul_f32_e32 v147, v85, v133
	v_mul_f32_e32 v133, v77, v133
	v_add_f32_e32 v136, 1.0, v136
	v_exp_f32_e32 v147, v147
	v_exp_f32_e32 v133, v133
	v_rcp_f32_e32 v136, v136
	v_add_f32_e32 v137, 1.0, v137
	v_add_f32_e32 v139, 1.0, v139
	v_rcp_f32_e32 v137, v137
	v_rcp_f32_e32 v139, v139
	v_add_f32_e32 v141, 1.0, v141
	v_rcp_f32_e32 v141, v141
	v_add_f32_e32 v143, 1.0, v143
	v_rcp_f32_e32 v143, v143
	v_add_f32_e32 v145, 1.0, v145
	v_rcp_f32_e32 v145, v145
	v_add_f32_e32 v147, 1.0, v147
	v_add_f32_e32 v133, 1.0, v133
	v_fma_f32 v136, v136, s55, 0.5
	v_rcp_f32_e32 v147, v147
	v_rcp_f32_e32 v133, v133
	v_cvt_pk_u8_f32 v136, v136, 0, 0
	v_fma_f32 v137, v137, s55, 0.5
	v_fma_f32 v139, v139, s55, 0.5
	v_cvt_pk_u8_f32 v137, v137, 0, 0
	v_cvt_pk_u8_f32 v136, v139, 1, v136
	v_fma_f32 v139, v141, s55, 0.5
	v_cvt_pk_u8_f32 v137, v139, 1, v137
	v_fma_f32 v139, v143, s55, 0.5
	v_cvt_pk_u8_f32 v136, v139, 2, v136
	v_fma_f32 v139, v145, s55, 0.5
	v_cvt_pk_u8_f32 v137, v139, 2, v137
	v_fma_f32 v139, v147, s55, 0.5
	v_fma_f32 v133, v133, s55, 0.5
	v_cvt_pk_u8_f32 v136, v139, 3, v136
	v_cvt_pk_u8_f32 v137, v133, 3, v137
	v_mul_f32_e32 v133, 0xbfb8aa3b, v142
	global_store_dwordx2 v[134:135], v[136:137], off offset:128 sc1
	v_mul_f32_e32 v136, v38, v133
	v_exp_f32_e32 v136, v136
	v_mul_f32_e32 v137, v34, v133
	v_mul_f32_e32 v139, v39, v133
	v_exp_f32_e32 v137, v137
	v_exp_f32_e32 v139, v139
	v_mul_f32_e32 v141, v35, v133
	v_exp_f32_e32 v141, v141
	v_mul_f32_e32 v143, v40, v133
	v_exp_f32_e32 v143, v143
	v_mul_f32_e32 v145, v36, v133
	v_exp_f32_e32 v145, v145
	v_mul_f32_e32 v147, v41, v133
	v_add_f32_e32 v136, 1.0, v136
	v_exp_f32_e32 v147, v147
	v_mul_f32_e32 v148, v37, v133
	v_rcp_f32_e32 v136, v136
	v_add_f32_e32 v137, 1.0, v137
	v_add_f32_e32 v139, 1.0, v139
	v_exp_f32_e32 v148, v148
	v_rcp_f32_e32 v137, v137
	v_rcp_f32_e32 v139, v139
	v_add_f32_e32 v141, 1.0, v141
	v_rcp_f32_e32 v141, v141
	v_add_f32_e32 v143, 1.0, v143
	v_rcp_f32_e32 v143, v143
	v_add_f32_e32 v145, 1.0, v145
	v_rcp_f32_e32 v145, v145
	v_add_f32_e32 v147, 1.0, v147
	v_fma_f32 v136, v136, s55, 0.5
	v_rcp_f32_e32 v147, v147
	v_add_f32_e32 v148, 1.0, v148
	v_cvt_pk_u8_f32 v136, v136, 0, 0
	v_fma_f32 v137, v137, s55, 0.5
	v_fma_f32 v139, v139, s55, 0.5
	v_rcp_f32_e32 v148, v148
	v_cvt_pk_u8_f32 v137, v137, 0, 0
	v_cvt_pk_u8_f32 v136, v139, 1, v136
	v_fma_f32 v139, v141, s55, 0.5
	v_add_u32_e32 v134, 0x90, v132
	v_cvt_pk_u8_f32 v137, v139, 1, v137
	v_fma_f32 v139, v143, s55, 0.5
	v_ashrrev_i32_e32 v135, 31, v134
	v_cvt_pk_u8_f32 v136, v139, 2, v136
	v_fma_f32 v139, v145, s55, 0.5
	v_lshlrev_b64 v[134:135], 10, v[134:135]
	v_cvt_pk_u8_f32 v137, v139, 2, v137
	v_fma_f32 v139, v147, s55, 0.5
	v_cvt_pk_u8_f32 v136, v139, 3, v136
	v_fma_f32 v139, v148, s55, 0.5
	v_lshl_add_u64 v[134:135], vcc, 0, v[134:135]
	v_cvt_pk_u8_f32 v137, v139, 3, v137
	v_lshl_add_u64 v[134:135], v[134:135], 0, v[130:131]
	global_store_dwordx2 v[134:135], v[136:137], off sc1
	v_mul_f32_e32 v136, v50, v133
	v_exp_f32_e32 v136, v136
	v_mul_f32_e32 v137, v42, v133
	v_mul_f32_e32 v139, v51, v133
	v_exp_f32_e32 v137, v137
	v_exp_f32_e32 v139, v139
	v_mul_f32_e32 v141, v43, v133
	v_exp_f32_e32 v141, v141
	v_mul_f32_e32 v143, v52, v133
	v_exp_f32_e32 v143, v143
	v_mul_f32_e32 v145, v44, v133
	v_exp_f32_e32 v145, v145
	v_mul_f32_e32 v147, v53, v133
	v_mul_f32_e32 v133, v45, v133
	v_add_f32_e32 v136, 1.0, v136
	v_exp_f32_e32 v147, v147
	v_exp_f32_e32 v133, v133
	v_rcp_f32_e32 v136, v136
	v_add_f32_e32 v137, 1.0, v137
	v_add_f32_e32 v139, 1.0, v139
	v_rcp_f32_e32 v137, v137
	v_rcp_f32_e32 v139, v139
	v_add_f32_e32 v141, 1.0, v141
	v_rcp_f32_e32 v141, v141
	v_add_f32_e32 v143, 1.0, v143
	v_rcp_f32_e32 v143, v143
	v_add_f32_e32 v145, 1.0, v145
	v_rcp_f32_e32 v145, v145
	v_add_f32_e32 v147, 1.0, v147
	v_add_f32_e32 v133, 1.0, v133
	v_fma_f32 v136, v136, s55, 0.5
	v_rcp_f32_e32 v147, v147
	v_rcp_f32_e32 v133, v133
	v_cvt_pk_u8_f32 v136, v136, 0, 0
	v_fma_f32 v137, v137, s55, 0.5
	v_fma_f32 v139, v139, s55, 0.5
	v_cvt_pk_u8_f32 v137, v137, 0, 0
	v_cvt_pk_u8_f32 v136, v139, 1, v136
	v_fma_f32 v139, v141, s55, 0.5
	v_cvt_pk_u8_f32 v137, v139, 1, v137
	v_fma_f32 v139, v143, s55, 0.5
	v_cvt_pk_u8_f32 v136, v139, 2, v136
	v_fma_f32 v139, v145, s55, 0.5
	v_cvt_pk_u8_f32 v137, v139, 2, v137
	v_fma_f32 v139, v147, s55, 0.5
	v_fma_f32 v133, v133, s55, 0.5
	v_cvt_pk_u8_f32 v136, v139, 3, v136
	v_cvt_pk_u8_f32 v137, v133, 3, v137
	v_mul_f32_e32 v133, 0xbfb8aa3b, v140
	global_store_dwordx2 v[134:135], v[136:137], off offset:128 sc1
	v_mul_f32_e32 v136, v22, v133
	v_exp_f32_e32 v136, v136
	v_mul_f32_e32 v137, v18, v133
	v_mul_f32_e32 v139, v23, v133
	v_exp_f32_e32 v137, v137
	v_exp_f32_e32 v139, v139
	v_mul_f32_e32 v141, v19, v133
	v_exp_f32_e32 v141, v141
	v_mul_f32_e32 v143, v24, v133
	v_exp_f32_e32 v143, v143
	v_mul_f32_e32 v145, v20, v133
	v_exp_f32_e32 v145, v145
	v_mul_f32_e32 v147, v25, v133
	v_add_f32_e32 v136, 1.0, v136
	v_exp_f32_e32 v147, v147
	v_mul_f32_e32 v148, v21, v133
	v_rcp_f32_e32 v136, v136
	v_add_f32_e32 v137, 1.0, v137
	v_add_f32_e32 v139, 1.0, v139
	v_exp_f32_e32 v148, v148
	v_rcp_f32_e32 v137, v137
	v_rcp_f32_e32 v139, v139
	v_add_f32_e32 v141, 1.0, v141
	v_rcp_f32_e32 v141, v141
	v_add_f32_e32 v143, 1.0, v143
	v_rcp_f32_e32 v143, v143
	v_add_f32_e32 v145, 1.0, v145
	v_rcp_f32_e32 v145, v145
	v_add_f32_e32 v147, 1.0, v147
	v_fma_f32 v136, v136, s55, 0.5
	v_rcp_f32_e32 v147, v147
	v_add_f32_e32 v148, 1.0, v148
	v_cvt_pk_u8_f32 v136, v136, 0, 0
	v_fma_f32 v137, v137, s55, 0.5
	v_fma_f32 v139, v139, s55, 0.5
	v_rcp_f32_e32 v148, v148
	v_cvt_pk_u8_f32 v137, v137, 0, 0
	v_cvt_pk_u8_f32 v136, v139, 1, v136
	v_fma_f32 v139, v141, s55, 0.5
	v_add_u32_e32 v134, 0xa0, v132
	v_cvt_pk_u8_f32 v137, v139, 1, v137
	v_fma_f32 v139, v143, s55, 0.5
	v_ashrrev_i32_e32 v135, 31, v134
	v_cvt_pk_u8_f32 v136, v139, 2, v136
	v_fma_f32 v139, v145, s55, 0.5
	v_lshlrev_b64 v[134:135], 10, v[134:135]
	v_cvt_pk_u8_f32 v137, v139, 2, v137
	v_fma_f32 v139, v147, s55, 0.5
	v_cvt_pk_u8_f32 v136, v139, 3, v136
	v_fma_f32 v139, v148, s55, 0.5
	v_lshl_add_u64 v[134:135], vcc, 0, v[134:135]
	v_cvt_pk_u8_f32 v137, v139, 3, v137
	v_lshl_add_u64 v[134:135], v[134:135], 0, v[130:131]
	global_store_dwordx2 v[134:135], v[136:137], off sc1
	v_mul_f32_e32 v136, v30, v133
	v_exp_f32_e32 v136, v136
	v_mul_f32_e32 v137, v26, v133
	v_mul_f32_e32 v139, v31, v133
	v_exp_f32_e32 v137, v137
	v_exp_f32_e32 v139, v139
	v_mul_f32_e32 v141, v27, v133
	v_exp_f32_e32 v141, v141
	v_mul_f32_e32 v143, v32, v133
	v_exp_f32_e32 v143, v143
	v_mul_f32_e32 v145, v28, v133
	v_exp_f32_e32 v145, v145
	v_mul_f32_e32 v147, v33, v133
	v_mul_f32_e32 v133, v29, v133
	v_add_f32_e32 v136, 1.0, v136
	v_exp_f32_e32 v147, v147
	v_exp_f32_e32 v133, v133
	v_rcp_f32_e32 v136, v136
	v_add_f32_e32 v137, 1.0, v137
	v_add_f32_e32 v139, 1.0, v139
	v_rcp_f32_e32 v137, v137
	v_rcp_f32_e32 v139, v139
	v_add_f32_e32 v141, 1.0, v141
	v_rcp_f32_e32 v141, v141
	v_add_f32_e32 v143, 1.0, v143
	v_rcp_f32_e32 v143, v143
	v_add_f32_e32 v145, 1.0, v145
	v_rcp_f32_e32 v145, v145
	v_add_f32_e32 v147, 1.0, v147
	v_add_f32_e32 v133, 1.0, v133
	v_fma_f32 v136, v136, s55, 0.5
	v_rcp_f32_e32 v147, v147
	v_rcp_f32_e32 v133, v133
	v_cvt_pk_u8_f32 v136, v136, 0, 0
	v_fma_f32 v137, v137, s55, 0.5
	v_fma_f32 v139, v139, s55, 0.5
	v_cvt_pk_u8_f32 v137, v137, 0, 0
	v_cvt_pk_u8_f32 v136, v139, 1, v136
	v_fma_f32 v139, v141, s55, 0.5
	v_cvt_pk_u8_f32 v137, v139, 1, v137
	v_fma_f32 v139, v143, s55, 0.5
	v_cvt_pk_u8_f32 v136, v139, 2, v136
	v_fma_f32 v139, v145, s55, 0.5
	v_cvt_pk_u8_f32 v137, v139, 2, v137
	v_fma_f32 v139, v147, s55, 0.5
	v_fma_f32 v133, v133, s55, 0.5
	v_cvt_pk_u8_f32 v136, v139, 3, v136
	v_cvt_pk_u8_f32 v137, v133, 3, v137
	global_store_dwordx2 v[134:135], v[136:137], off offset:128 sc1
	v_mul_f32_e32 v136, 0xbfb8aa3b, v138
	v_mul_f32_e32 v134, v6, v136
	v_exp_f32_e32 v134, v134
	v_mul_f32_e32 v135, v2, v136
	v_mul_f32_e32 v137, v7, v136
	v_exp_f32_e32 v135, v135
	v_exp_f32_e32 v137, v137
	v_mul_f32_e32 v139, v3, v136
	v_exp_f32_e32 v139, v139
	v_mul_f32_e32 v141, v8, v136
	v_exp_f32_e32 v141, v141
	v_mul_f32_e32 v143, v4, v136
	v_exp_f32_e32 v143, v143
	v_mul_f32_e32 v145, v9, v136
	v_add_f32_e32 v134, 1.0, v134
	v_exp_f32_e32 v145, v145
	v_mul_f32_e32 v147, v5, v136
	v_rcp_f32_e32 v134, v134
	v_add_f32_e32 v135, 1.0, v135
	v_add_f32_e32 v137, 1.0, v137
	v_exp_f32_e32 v147, v147
	v_rcp_f32_e32 v135, v135
	v_rcp_f32_e32 v137, v137
	v_add_f32_e32 v139, 1.0, v139
	v_rcp_f32_e32 v139, v139
	v_add_f32_e32 v141, 1.0, v141
	v_rcp_f32_e32 v141, v141
	v_add_f32_e32 v143, 1.0, v143
	v_rcp_f32_e32 v143, v143
	v_add_f32_e32 v145, 1.0, v145
	v_fma_f32 v134, v134, s55, 0.5
	v_rcp_f32_e32 v145, v145
	v_add_f32_e32 v147, 1.0, v147
	v_cvt_pk_u8_f32 v134, v134, 0, 0
	v_fma_f32 v135, v135, s55, 0.5
	v_fma_f32 v137, v137, s55, 0.5
	v_rcp_f32_e32 v147, v147
	v_cvt_pk_u8_f32 v135, v135, 0, 0
	v_cvt_pk_u8_f32 v134, v137, 1, v134
	v_fma_f32 v137, v139, s55, 0.5
	v_add_u32_e32 v132, 0xb0, v132
	v_cvt_pk_u8_f32 v135, v137, 1, v135
	v_fma_f32 v137, v141, s55, 0.5
	v_ashrrev_i32_e32 v133, 31, v132
	v_cvt_pk_u8_f32 v134, v137, 2, v134
	v_fma_f32 v137, v143, s55, 0.5
	v_lshlrev_b64 v[132:133], 10, v[132:133]
	v_cvt_pk_u8_f32 v135, v137, 2, v135
	v_fma_f32 v137, v145, s55, 0.5
	v_cvt_pk_u8_f32 v134, v137, 3, v134
	v_fma_f32 v137, v147, s55, 0.5
	v_lshl_add_u64 v[132:133], vcc, 0, v[132:133]
	v_cvt_pk_u8_f32 v135, v137, 3, v135
	v_lshl_add_u64 v[130:131], v[132:133], 0, v[130:131]
	v_mul_f32_e32 v132, v14, v136
	global_store_dwordx2 v[130:131], v[134:135], off sc1
	v_exp_f32_e32 v132, v132
	v_mul_f32_e32 v133, v10, v136
	v_mul_f32_e32 v134, v15, v136
	v_exp_f32_e32 v133, v133
	v_exp_f32_e32 v134, v134
	v_mul_f32_e32 v135, v11, v136
	v_exp_f32_e32 v135, v135
	v_mul_f32_e32 v137, v16, v136
	v_exp_f32_e32 v137, v137
	v_mul_f32_e32 v139, v12, v136
	v_exp_f32_e32 v139, v139
	v_mul_f32_e32 v141, v17, v136
	v_add_f32_e32 v132, 1.0, v132
	v_exp_f32_e32 v141, v141
	v_mul_f32_e32 v136, v13, v136
	v_rcp_f32_e32 v132, v132
	v_add_f32_e32 v133, 1.0, v133
	v_add_f32_e32 v134, 1.0, v134
	v_exp_f32_e32 v136, v136
	v_rcp_f32_e32 v133, v133
	v_rcp_f32_e32 v134, v134
	v_add_f32_e32 v135, 1.0, v135
	v_rcp_f32_e32 v135, v135
	v_add_f32_e32 v137, 1.0, v137
	v_rcp_f32_e32 v137, v137
	v_add_f32_e32 v139, 1.0, v139
	v_rcp_f32_e32 v139, v139
	v_add_f32_e32 v141, 1.0, v141
	v_fma_f32 v132, v132, s55, 0.5
	v_rcp_f32_e32 v141, v141
	v_add_f32_e32 v136, 1.0, v136
	v_cvt_pk_u8_f32 v132, v132, 0, 0
	v_fma_f32 v133, v133, s55, 0.5
	v_fma_f32 v134, v134, s55, 0.5
	v_rcp_f32_e32 v136, v136
	v_cvt_pk_u8_f32 v133, v133, 0, 0
	v_cvt_pk_u8_f32 v132, v134, 1, v132
	v_fma_f32 v134, v135, s55, 0.5
	v_cvt_pk_u8_f32 v133, v134, 1, v133
	v_fma_f32 v134, v137, s55, 0.5
	v_cvt_pk_u8_f32 v132, v134, 2, v132
	v_fma_f32 v134, v139, s55, 0.5
	v_cvt_pk_u8_f32 v133, v134, 2, v133
	v_fma_f32 v134, v141, s55, 0.5
	v_cvt_pk_u8_f32 v132, v134, 3, v132
	v_fma_f32 v134, v136, s55, 0.5
	v_cvt_pk_u8_f32 v133, v134, 3, v133
	global_store_dwordx2 v[130:131], v[132:133], off offset:128 sc1

.LBB0_761:
	s_andn2_b64 vcc, exec, s[46:47]
	s_cbranch_vccnz .LBB0_763
	s_lshl_b32 s2, s24, 8
	s_add_i32 s2, s2, s16
	v_add_u32_e32 v130, s2, v183
	s_lshl_b32 s2, s40, 8
	s_and_b32 s2, s2, 0x300
	s_or_b32 s2, s2, s83
	v_lshl_add_u32 v131, v182, 3, s2
	v_ashrrev_i32_e32 v139, 4, v131
	v_add_u32_e32 v131, 0x80, v131
	v_ashrrev_i32_e32 v141, 4, v131
	v_ashrrev_i32_e32 v131, 31, v130
	v_pk_mul_f32 v[134:135], v[120:121], v[158:159] op_sel_hi:[1,0]
	v_pk_mul_f32 v[132:133], v[118:119], v[158:159] op_sel_hi:[1,0]
	v_pk_mul_f32 v[136:137], v[116:117], v[158:159] op_sel_hi:[1,0]
	v_pk_mul_f32 v[148:149], v[114:115], v[158:159] op_sel_hi:[1,0]
	v_cvt_pk_bf16_f32 v132, v132, v133
	v_cvt_pk_bf16_f32 v133, v134, v135
	v_lshlrev_b32_e32 v143, 4, v182
	v_cvt_pk_bf16_f32 v134, v148, v149
	v_cvt_pk_bf16_f32 v135, v136, v137
	v_mad_i64_i32 v[136:137], s[12:13], v139, s56, v[130:131]
	v_lshlrev_b64 v[136:137], 5, v[136:137]
	v_lshl_add_u64 v[136:137], s[4:5], 0, v[136:137]
	v_and_b32_e32 v166, 16, v143
	v_lshl_add_u64 v[136:137], v[136:137], 0, v[166:167]
	global_store_dwordx4 v[136:137], v[132:135], off sc1
	v_pk_mul_f32 v[136:137], v[124:125], v[158:159] op_sel_hi:[1,0]
	v_pk_mul_f32 v[148:149], v[122:123], v[158:159] op_sel_hi:[1,0]
	v_pk_mul_f32 v[134:135], v[128:129], v[158:159] op_sel_hi:[1,0]
	v_pk_mul_f32 v[132:133], v[126:127], v[158:159] op_sel_hi:[1,0]
	v_pk_mul_f32 v[152:153], v[98:99], v[154:155] op_sel_hi:[1,0]
	v_cvt_pk_bf16_f32 v132, v132, v133
	v_cvt_pk_bf16_f32 v133, v134, v135
	v_cvt_pk_bf16_f32 v134, v148, v149
	v_cvt_pk_bf16_f32 v135, v136, v137
	v_mad_i64_i32 v[136:137], s[12:13], v141, s56, v[130:131]
	v_lshlrev_b64 v[136:137], 5, v[136:137]
	v_lshl_add_u64 v[136:137], s[4:5], 0, v[136:137]
	v_lshl_add_u64 v[136:137], v[136:137], 0, v[166:167]
	global_store_dwordx4 v[136:137], v[132:135], off sc1
	v_add_u32_e32 v136, 16, v130
	v_ashrrev_i32_e32 v137, 31, v136
	v_pk_mul_f32 v[134:135], v[104:105], v[154:155] op_sel_hi:[1,0]
	v_pk_mul_f32 v[132:133], v[102:103], v[154:155] op_sel_hi:[1,0]
	v_pk_mul_f32 v[148:149], v[100:101], v[154:155] op_sel_hi:[1,0]
	v_cvt_pk_bf16_f32 v132, v132, v133
	v_cvt_pk_bf16_f32 v133, v134, v135
	v_cvt_pk_bf16_f32 v134, v152, v153
	v_pk_mul_f32 v[152:153], v[106:107], v[154:155] op_sel_hi:[1,0]
	v_cvt_pk_bf16_f32 v135, v148, v149
	v_mad_i64_i32 v[148:149], s[12:13], v139, s56, v[136:137]
	v_lshlrev_b64 v[148:149], 5, v[148:149]
	v_mad_i64_i32 v[136:137], s[12:13], v141, s56, v[136:137]
	v_lshl_add_u64 v[148:149], s[4:5], 0, v[148:149]
	v_lshlrev_b64 v[136:137], 5, v[136:137]
	v_lshl_add_u64 v[148:149], v[148:149], 0, v[166:167]
	v_lshl_add_u64 v[136:137], s[4:5], 0, v[136:137]
	global_store_dwordx4 v[148:149], v[132:135], off sc1
	v_lshl_add_u64 v[136:137], v[136:137], 0, v[166:167]
	v_pk_mul_f32 v[148:149], v[108:109], v[154:155] op_sel_hi:[1,0]
	v_pk_mul_f32 v[134:135], v[112:113], v[154:155] op_sel_hi:[1,0]
	v_pk_mul_f32 v[132:133], v[110:111], v[154:155] op_sel_hi:[1,0]
	s_nop 0
	v_cvt_pk_bf16_f32 v132, v132, v133
	v_cvt_pk_bf16_f32 v133, v134, v135
	v_cvt_pk_bf16_f32 v134, v152, v153
	v_cvt_pk_bf16_f32 v135, v148, v149
	global_store_dwordx4 v[136:137], v[132:135], off sc1
	v_add_u32_e32 v136, 32, v130
	v_ashrrev_i32_e32 v137, 31, v136
	v_pk_mul_f32 v[134:135], v[88:89], v[150:151] op_sel_hi:[1,0]
	v_pk_mul_f32 v[132:133], v[86:87], v[150:151] op_sel_hi:[1,0]
	v_pk_mul_f32 v[148:149], v[80:81], v[150:151] op_sel_hi:[1,0]
	v_pk_mul_f32 v[152:153], v[78:79], v[150:151] op_sel_hi:[1,0]
	v_cvt_pk_bf16_f32 v132, v132, v133
	v_cvt_pk_bf16_f32 v133, v134, v135
	s_nop 0
	v_cvt_pk_bf16_f32 v134, v152, v153
	v_cvt_pk_bf16_f32 v135, v148, v149
	v_mad_i64_i32 v[148:149], s[12:13], v139, s56, v[136:137]
	v_lshlrev_b64 v[148:149], 5, v[148:149]
	v_mad_i64_i32 v[136:137], s[12:13], v141, s56, v[136:137]
	v_lshl_add_u64 v[148:149], s[4:5], 0, v[148:149]
	v_lshlrev_b64 v[136:137], 5, v[136:137]
	v_lshl_add_u64 v[148:149], v[148:149], 0, v[166:167]
	v_lshl_add_u64 v[136:137], s[4:5], 0, v[136:137]
	global_store_dwordx4 v[148:149], v[132:135], off sc1
	v_lshl_add_u64 v[136:137], v[136:137], 0, v[166:167]
	v_pk_mul_f32 v[148:149], v[92:93], v[150:151] op_sel_hi:[1,0]
	v_pk_mul_f32 v[134:135], v[96:97], v[150:151] op_sel_hi:[1,0]
	v_pk_mul_f32 v[132:133], v[94:95], v[150:151] op_sel_hi:[1,0]
	v_pk_mul_f32 v[152:153], v[90:91], v[150:151] op_sel_hi:[1,0]
	v_cvt_pk_bf16_f32 v132, v132, v133
	v_cvt_pk_bf16_f32 v133, v134, v135
	s_nop 0
	v_cvt_pk_bf16_f32 v134, v152, v153
	v_cvt_pk_bf16_f32 v135, v148, v149
	global_store_dwordx4 v[136:137], v[132:135], off sc1
	v_add_u32_e32 v136, 48, v130
	v_ashrrev_i32_e32 v137, 31, v136
	v_pk_mul_f32 v[134:135], v[56:57], v[146:147] op_sel_hi:[1,0]
	v_pk_mul_f32 v[132:133], v[54:55], v[146:147] op_sel_hi:[1,0]
	v_pk_mul_f32 v[148:149], v[48:49], v[146:147] op_sel_hi:[1,0]
	v_pk_mul_f32 v[152:153], v[46:47], v[146:147] op_sel_hi:[1,0]
	v_cvt_pk_bf16_f32 v132, v132, v133
	v_cvt_pk_bf16_f32 v133, v134, v135
	s_nop 0
	v_cvt_pk_bf16_f32 v134, v152, v153
	v_cvt_pk_bf16_f32 v135, v148, v149
	v_mad_i64_i32 v[148:149], s[12:13], v139, s56, v[136:137]
	v_lshlrev_b64 v[148:149], 5, v[148:149]
	v_mad_i64_i32 v[136:137], s[12:13], v141, s56, v[136:137]
	v_lshl_add_u64 v[148:149], s[4:5], 0, v[148:149]
	v_lshlrev_b64 v[136:137], 5, v[136:137]
	v_lshl_add_u64 v[148:149], v[148:149], 0, v[166:167]
	v_lshl_add_u64 v[136:137], s[4:5], 0, v[136:137]
	global_store_dwordx4 v[148:149], v[132:135], off sc1
	v_lshl_add_u64 v[136:137], v[136:137], 0, v[166:167]
	v_pk_mul_f32 v[148:149], v[60:61], v[146:147] op_sel_hi:[1,0]
	v_pk_mul_f32 v[134:135], v[68:69], v[146:147] op_sel_hi:[1,0]
	v_pk_mul_f32 v[132:133], v[66:67], v[146:147] op_sel_hi:[1,0]
	v_pk_mul_f32 v[152:153], v[58:59], v[146:147] op_sel_hi:[1,0]
	v_cvt_pk_bf16_f32 v132, v132, v133
	v_cvt_pk_bf16_f32 v133, v134, v135
	s_nop 0
	v_cvt_pk_bf16_f32 v134, v152, v153
	v_cvt_pk_bf16_f32 v135, v148, v149
	global_store_dwordx4 v[136:137], v[132:135], off sc1
	v_add_u32_e32 v136, 0x80, v130
	v_ashrrev_i32_e32 v137, 31, v136
	v_pk_mul_f32 v[134:135], v[72:73], v[144:145] op_sel_hi:[1,0]
	v_pk_mul_f32 v[132:133], v[70:71], v[144:145] op_sel_hi:[1,0]
	v_pk_mul_f32 v[148:149], v[64:65], v[144:145] op_sel_hi:[1,0]
	v_pk_mul_f32 v[152:153], v[62:63], v[144:145] op_sel_hi:[1,0]
	v_cvt_pk_bf16_f32 v132, v132, v133
	v_cvt_pk_bf16_f32 v133, v134, v135
	s_nop 0
	v_cvt_pk_bf16_f32 v134, v152, v153
	v_cvt_pk_bf16_f32 v135, v148, v149
	v_mad_i64_i32 v[148:149], s[12:13], v139, s56, v[136:137]
	v_lshlrev_b64 v[148:149], 5, v[148:149]
	v_mad_i64_i32 v[136:137], s[12:13], v141, s56, v[136:137]
	v_lshl_add_u64 v[148:149], s[4:5], 0, v[148:149]
	v_lshlrev_b64 v[136:137], 5, v[136:137]
	v_lshl_add_u64 v[148:149], v[148:149], 0, v[166:167]
	v_lshl_add_u64 v[136:137], s[4:5], 0, v[136:137]
	global_store_dwordx4 v[148:149], v[132:135], off sc1
	v_lshl_add_u64 v[136:137], v[136:137], 0, v[166:167]
	v_pk_mul_f32 v[148:149], v[76:77], v[144:145] op_sel_hi:[1,0]
	v_pk_mul_f32 v[134:135], v[84:85], v[144:145] op_sel_hi:[1,0]
	v_pk_mul_f32 v[132:133], v[82:83], v[144:145] op_sel_hi:[1,0]
	v_pk_mul_f32 v[152:153], v[74:75], v[144:145] op_sel_hi:[1,0]
	v_cvt_pk_bf16_f32 v132, v132, v133
	v_cvt_pk_bf16_f32 v133, v134, v135
	s_nop 0
	v_cvt_pk_bf16_f32 v134, v152, v153
	v_cvt_pk_bf16_f32 v135, v148, v149
	global_store_dwordx4 v[136:137], v[132:135], off sc1
	v_add_u32_e32 v136, 0x90, v130
	v_ashrrev_i32_e32 v137, 31, v136
	v_pk_mul_f32 v[134:135], v[40:41], v[142:143] op_sel_hi:[1,0]
	v_pk_mul_f32 v[132:133], v[38:39], v[142:143] op_sel_hi:[1,0]
	v_pk_mul_f32 v[148:149], v[36:37], v[142:143] op_sel_hi:[1,0]
	v_pk_mul_f32 v[152:153], v[34:35], v[142:143] op_sel_hi:[1,0]
	v_cvt_pk_bf16_f32 v132, v132, v133
	v_cvt_pk_bf16_f32 v133, v134, v135
	s_nop 0
	v_cvt_pk_bf16_f32 v134, v152, v153
	v_cvt_pk_bf16_f32 v135, v148, v149
	v_mad_i64_i32 v[148:149], s[12:13], v139, s56, v[136:137]
	v_lshlrev_b64 v[148:149], 5, v[148:149]
	v_mad_i64_i32 v[136:137], s[12:13], v141, s56, v[136:137]
	v_lshl_add_u64 v[148:149], s[4:5], 0, v[148:149]
	v_lshlrev_b64 v[136:137], 5, v[136:137]
	v_lshl_add_u64 v[148:149], v[148:149], 0, v[166:167]
	v_lshl_add_u64 v[136:137], s[4:5], 0, v[136:137]
	global_store_dwordx4 v[148:149], v[132:135], off sc1
	v_lshl_add_u64 v[136:137], v[136:137], 0, v[166:167]
	v_pk_mul_f32 v[148:149], v[44:45], v[142:143] op_sel_hi:[1,0]
	v_pk_mul_f32 v[134:135], v[52:53], v[142:143] op_sel_hi:[1,0]
	v_pk_mul_f32 v[132:133], v[50:51], v[142:143] op_sel_hi:[1,0]
	v_pk_mul_f32 v[152:153], v[42:43], v[142:143] op_sel_hi:[1,0]
	v_cvt_pk_bf16_f32 v132, v132, v133
	v_cvt_pk_bf16_f32 v133, v134, v135
	s_nop 0
	v_cvt_pk_bf16_f32 v134, v152, v153
	v_cvt_pk_bf16_f32 v135, v148, v149
	global_store_dwordx4 v[136:137], v[132:135], off sc1
	v_add_u32_e32 v136, 0xa0, v130
	v_ashrrev_i32_e32 v137, 31, v136
	v_pk_mul_f32 v[134:135], v[24:25], v[140:141] op_sel_hi:[1,0]
	v_pk_mul_f32 v[132:133], v[22:23], v[140:141] op_sel_hi:[1,0]
	v_pk_mul_f32 v[148:149], v[20:21], v[140:141] op_sel_hi:[1,0]
	v_pk_mul_f32 v[152:153], v[18:19], v[140:141] op_sel_hi:[1,0]
	v_cvt_pk_bf16_f32 v132, v132, v133
	v_cvt_pk_bf16_f32 v133, v134, v135
	s_nop 0
	v_cvt_pk_bf16_f32 v134, v152, v153
	v_cvt_pk_bf16_f32 v135, v148, v149
	v_mad_i64_i32 v[148:149], s[12:13], v139, s56, v[136:137]
	v_lshlrev_b64 v[148:149], 5, v[148:149]
	v_lshl_add_u64 v[148:149], s[4:5], 0, v[148:149]
	v_mad_i64_i32 v[136:137], s[12:13], v141, s56, v[136:137]
	v_lshl_add_u64 v[148:149], v[148:149], 0, v[166:167]
	v_lshlrev_b64 v[136:137], 5, v[136:137]
	global_store_dwordx4 v[148:149], v[132:135], off sc1
	v_lshl_add_u64 v[136:137], s[4:5], 0, v[136:137]
	v_pk_mul_f32 v[152:153], v[26:27], v[140:141] op_sel_hi:[1,0]
	v_pk_mul_f32 v[134:135], v[32:33], v[140:141] op_sel_hi:[1,0]
	v_pk_mul_f32 v[132:133], v[30:31], v[140:141] op_sel_hi:[1,0]
	v_lshl_add_u64 v[136:137], v[136:137], 0, v[166:167]
	v_cvt_pk_bf16_f32 v132, v132, v133
	v_cvt_pk_bf16_f32 v133, v134, v135
	v_cvt_pk_bf16_f32 v134, v152, v153
	v_pk_mul_f32 v[148:149], v[28:29], v[140:141] op_sel_hi:[1,0]
	s_nop 0
	v_cvt_pk_bf16_f32 v135, v148, v149
	global_store_dwordx4 v[136:137], v[132:135], off sc1
	v_pk_mul_f32 v[136:137], v[4:5], v[138:139] op_sel_hi:[1,0]
	v_pk_mul_f32 v[148:149], v[2:3], v[138:139] op_sel_hi:[1,0]
	v_add_u32_e32 v134, 0xb0, v130
	v_ashrrev_i32_e32 v135, 31, v134
	v_pk_mul_f32 v[132:133], v[8:9], v[138:139] op_sel_hi:[1,0]
	v_pk_mul_f32 v[130:131], v[6:7], v[138:139] op_sel_hi:[1,0]
	s_nop 0
	v_cvt_pk_bf16_f32 v130, v130, v131
	v_cvt_pk_bf16_f32 v131, v132, v133
	v_cvt_pk_bf16_f32 v132, v148, v149
	v_cvt_pk_bf16_f32 v133, v136, v137
	v_mad_i64_i32 v[136:137], s[12:13], v139, s56, v[134:135]
	v_lshlrev_b64 v[136:137], 5, v[136:137]
	v_mad_i64_i32 v[134:135], s[12:13], v141, s56, v[134:135]
	v_lshl_add_u64 v[136:137], s[4:5], 0, v[136:137]
	v_lshlrev_b64 v[134:135], 5, v[134:135]
	v_lshl_add_u64 v[136:137], v[136:137], 0, v[166:167]
	v_lshl_add_u64 v[134:135], s[4:5], 0, v[134:135]
	global_store_dwordx4 v[136:137], v[130:133], off sc1
	v_lshl_add_u64 v[134:135], v[134:135], 0, v[166:167]
	v_pk_mul_f32 v[136:137], v[12:13], v[138:139] op_sel_hi:[1,0]
	v_pk_mul_f32 v[132:133], v[16:17], v[138:139] op_sel_hi:[1,0]
	v_pk_mul_f32 v[130:131], v[14:15], v[138:139] op_sel_hi:[1,0]
	v_pk_mul_f32 v[148:149], v[10:11], v[138:139] op_sel_hi:[1,0]
	v_cvt_pk_bf16_f32 v130, v130, v131
	v_cvt_pk_bf16_f32 v131, v132, v133
	s_nop 0
	v_cvt_pk_bf16_f32 v132, v148, v149
	v_cvt_pk_bf16_f32 v133, v136, v137
	global_store_dwordx4 v[134:135], v[130:133], off sc1

.LBB0_764:
	s_andn2_b64 vcc, exec, s[46:47]
	s_cbranch_vccnz .LBB0_769
	s_cmp_gt_i32 s41, 0
	s_mov_b64 s[46:47], -1
	s_cbranch_scc0 .LBB0_767
	s_lshl_b32 s2, s24, 8
	s_add_i32 s2, s2, s16
	v_add_u32_e32 v130, s2, v183
	s_lshl_b32 s2, s40, 8
	s_and_b32 s2, s2, 0x300
	s_or_b32 s2, s2, s83
	v_lshl_add_u32 v132, v182, 3, s2
	v_ashrrev_i32_e32 v131, 31, v130
	v_ashrrev_i32_e32 v133, 31, v132
	v_lshlrev_b64 v[148:149], 11, v[130:131]
	v_pk_mul_f32 v[134:135], v[118:119], v[158:159] op_sel_hi:[1,0]
	v_lshl_add_u64 v[148:149], s[8:9], 0, v[148:149]
	v_lshlrev_b64 v[132:133], 1, v[132:133]
	v_pk_mul_f32 v[136:137], v[120:121], v[158:159] op_sel_hi:[1,0]
	v_cvt_pk_bf16_f32 v134, v134, v135
	v_lshl_add_u64 v[148:149], v[148:149], 0, v[132:133]
	v_cvt_pk_bf16_f32 v135, v136, v137
	v_pk_mul_f32 v[152:153], v[116:117], v[158:159] op_sel_hi:[1,0]
	v_pk_mul_f32 v[156:157], v[114:115], v[158:159] op_sel_hi:[1,0]
	s_mov_b64 s[46:47], 0
	v_cvt_pk_bf16_f32 v136, v156, v157
	v_cvt_pk_bf16_f32 v137, v152, v153
	global_store_dwordx4 v[148:149], v[134:137], off sc1
	v_pk_mul_f32 v[152:153], v[124:125], v[158:159] op_sel_hi:[1,0]
	v_pk_mul_f32 v[156:157], v[122:123], v[158:159] op_sel_hi:[1,0]
	v_pk_mul_f32 v[134:135], v[126:127], v[158:159] op_sel_hi:[1,0]
	v_pk_mul_f32 v[136:137], v[128:129], v[158:159] op_sel_hi:[1,0]
	v_cvt_pk_bf16_f32 v134, v134, v135
	s_nop 0
	v_cvt_pk_bf16_f32 v135, v136, v137
	v_cvt_pk_bf16_f32 v136, v156, v157
	v_cvt_pk_bf16_f32 v137, v152, v153
	global_store_dwordx4 v[148:149], v[134:137], off offset:256 sc1
	v_pk_mul_f32 v[152:153], v[100:101], v[154:155] op_sel_hi:[1,0]
	v_pk_mul_f32 v[156:157], v[98:99], v[154:155] op_sel_hi:[1,0]
	v_add_u32_e32 v134, 16, v130
	v_ashrrev_i32_e32 v135, 31, v134
	v_lshlrev_b64 v[148:149], 11, v[134:135]
	v_pk_mul_f32 v[134:135], v[102:103], v[154:155] op_sel_hi:[1,0]
	v_lshl_add_u64 v[148:149], s[8:9], 0, v[148:149]
	v_pk_mul_f32 v[136:137], v[104:105], v[154:155] op_sel_hi:[1,0]
	v_cvt_pk_bf16_f32 v134, v134, v135
	v_lshl_add_u64 v[148:149], v[148:149], 0, v[132:133]
	v_cvt_pk_bf16_f32 v135, v136, v137
	v_cvt_pk_bf16_f32 v136, v156, v157
	v_cvt_pk_bf16_f32 v137, v152, v153
	global_store_dwordx4 v[148:149], v[134:137], off sc1
	v_pk_mul_f32 v[152:153], v[108:109], v[154:155] op_sel_hi:[1,0]
	v_pk_mul_f32 v[156:157], v[106:107], v[154:155] op_sel_hi:[1,0]
	v_pk_mul_f32 v[134:135], v[110:111], v[154:155] op_sel_hi:[1,0]
	v_pk_mul_f32 v[136:137], v[112:113], v[154:155] op_sel_hi:[1,0]
	v_cvt_pk_bf16_f32 v134, v134, v135
	s_nop 0
	v_cvt_pk_bf16_f32 v135, v136, v137
	v_cvt_pk_bf16_f32 v136, v156, v157
	v_cvt_pk_bf16_f32 v137, v152, v153
	global_store_dwordx4 v[148:149], v[134:137], off offset:256 sc1
	v_pk_mul_f32 v[152:153], v[80:81], v[150:151] op_sel_hi:[1,0]
	v_pk_mul_f32 v[156:157], v[78:79], v[150:151] op_sel_hi:[1,0]
	v_add_u32_e32 v134, 32, v130
	v_ashrrev_i32_e32 v135, 31, v134
	v_lshlrev_b64 v[148:149], 11, v[134:135]
	v_pk_mul_f32 v[134:135], v[86:87], v[150:151] op_sel_hi:[1,0]
	v_lshl_add_u64 v[148:149], s[8:9], 0, v[148:149]
	v_pk_mul_f32 v[136:137], v[88:89], v[150:151] op_sel_hi:[1,0]
	v_cvt_pk_bf16_f32 v134, v134, v135
	v_lshl_add_u64 v[148:149], v[148:149], 0, v[132:133]
	v_cvt_pk_bf16_f32 v135, v136, v137
	v_cvt_pk_bf16_f32 v136, v156, v157
	v_cvt_pk_bf16_f32 v137, v152, v153
	global_store_dwordx4 v[148:149], v[134:137], off sc1
	v_pk_mul_f32 v[152:153], v[92:93], v[150:151] op_sel_hi:[1,0]
	v_pk_mul_f32 v[156:157], v[90:91], v[150:151] op_sel_hi:[1,0]
	v_pk_mul_f32 v[134:135], v[94:95], v[150:151] op_sel_hi:[1,0]
	v_pk_mul_f32 v[136:137], v[96:97], v[150:151] op_sel_hi:[1,0]
	v_cvt_pk_bf16_f32 v134, v134, v135
	s_nop 0
	v_cvt_pk_bf16_f32 v135, v136, v137
	v_cvt_pk_bf16_f32 v136, v156, v157
	v_cvt_pk_bf16_f32 v137, v152, v153
	global_store_dwordx4 v[148:149], v[134:137], off offset:256 sc1
	v_pk_mul_f32 v[152:153], v[48:49], v[146:147] op_sel_hi:[1,0]
	v_pk_mul_f32 v[156:157], v[46:47], v[146:147] op_sel_hi:[1,0]
	v_add_u32_e32 v134, 48, v130
	v_ashrrev_i32_e32 v135, 31, v134
	v_lshlrev_b64 v[148:149], 11, v[134:135]
	v_pk_mul_f32 v[134:135], v[54:55], v[146:147] op_sel_hi:[1,0]
	v_lshl_add_u64 v[148:149], s[8:9], 0, v[148:149]
	v_pk_mul_f32 v[136:137], v[56:57], v[146:147] op_sel_hi:[1,0]
	v_cvt_pk_bf16_f32 v134, v134, v135
	v_lshl_add_u64 v[148:149], v[148:149], 0, v[132:133]
	v_cvt_pk_bf16_f32 v135, v136, v137
	v_cvt_pk_bf16_f32 v136, v156, v157
	v_cvt_pk_bf16_f32 v137, v152, v153
	global_store_dwordx4 v[148:149], v[134:137], off sc1
	v_pk_mul_f32 v[152:153], v[60:61], v[146:147] op_sel_hi:[1,0]
	v_pk_mul_f32 v[156:157], v[58:59], v[146:147] op_sel_hi:[1,0]
	v_pk_mul_f32 v[134:135], v[66:67], v[146:147] op_sel_hi:[1,0]
	v_pk_mul_f32 v[136:137], v[68:69], v[146:147] op_sel_hi:[1,0]
	v_cvt_pk_bf16_f32 v134, v134, v135
	s_nop 0
	v_cvt_pk_bf16_f32 v135, v136, v137
	v_cvt_pk_bf16_f32 v136, v156, v157
	v_cvt_pk_bf16_f32 v137, v152, v153
	global_store_dwordx4 v[148:149], v[134:137], off offset:256 sc1
	v_pk_mul_f32 v[152:153], v[64:65], v[144:145] op_sel_hi:[1,0]
	v_pk_mul_f32 v[156:157], v[62:63], v[144:145] op_sel_hi:[1,0]
	v_add_u32_e32 v134, 0x80, v130
	v_ashrrev_i32_e32 v135, 31, v134
	v_lshlrev_b64 v[148:149], 11, v[134:135]
	v_pk_mul_f32 v[134:135], v[70:71], v[144:145] op_sel_hi:[1,0]
	v_lshl_add_u64 v[148:149], s[8:9], 0, v[148:149]
	v_pk_mul_f32 v[136:137], v[72:73], v[144:145] op_sel_hi:[1,0]
	v_cvt_pk_bf16_f32 v134, v134, v135
	v_lshl_add_u64 v[148:149], v[148:149], 0, v[132:133]
	v_cvt_pk_bf16_f32 v135, v136, v137
	v_cvt_pk_bf16_f32 v136, v156, v157
	v_cvt_pk_bf16_f32 v137, v152, v153
	global_store_dwordx4 v[148:149], v[134:137], off sc1
	v_pk_mul_f32 v[152:153], v[76:77], v[144:145] op_sel_hi:[1,0]
	v_pk_mul_f32 v[156:157], v[74:75], v[144:145] op_sel_hi:[1,0]
	v_pk_mul_f32 v[134:135], v[82:83], v[144:145] op_sel_hi:[1,0]
	v_pk_mul_f32 v[136:137], v[84:85], v[144:145] op_sel_hi:[1,0]
	v_cvt_pk_bf16_f32 v134, v134, v135
	s_nop 0
	v_cvt_pk_bf16_f32 v135, v136, v137
	v_cvt_pk_bf16_f32 v136, v156, v157
	v_cvt_pk_bf16_f32 v137, v152, v153
	global_store_dwordx4 v[148:149], v[134:137], off offset:256 sc1
	v_pk_mul_f32 v[152:153], v[36:37], v[142:143] op_sel_hi:[1,0]
	v_pk_mul_f32 v[156:157], v[34:35], v[142:143] op_sel_hi:[1,0]
	v_add_u32_e32 v134, 0x90, v130
	v_ashrrev_i32_e32 v135, 31, v134
	v_lshlrev_b64 v[148:149], 11, v[134:135]
	v_pk_mul_f32 v[134:135], v[38:39], v[142:143] op_sel_hi:[1,0]
	v_lshl_add_u64 v[148:149], s[8:9], 0, v[148:149]
	v_pk_mul_f32 v[136:137], v[40:41], v[142:143] op_sel_hi:[1,0]
	v_cvt_pk_bf16_f32 v134, v134, v135
	v_lshl_add_u64 v[148:149], v[148:149], 0, v[132:133]
	v_cvt_pk_bf16_f32 v135, v136, v137
	v_cvt_pk_bf16_f32 v136, v156, v157
	v_cvt_pk_bf16_f32 v137, v152, v153
	global_store_dwordx4 v[148:149], v[134:137], off sc1
	v_pk_mul_f32 v[152:153], v[44:45], v[142:143] op_sel_hi:[1,0]
	v_pk_mul_f32 v[156:157], v[42:43], v[142:143] op_sel_hi:[1,0]
	v_pk_mul_f32 v[134:135], v[50:51], v[142:143] op_sel_hi:[1,0]
	v_pk_mul_f32 v[136:137], v[52:53], v[142:143] op_sel_hi:[1,0]
	v_cvt_pk_bf16_f32 v134, v134, v135
	s_nop 0
	v_cvt_pk_bf16_f32 v135, v136, v137
	v_cvt_pk_bf16_f32 v136, v156, v157
	v_cvt_pk_bf16_f32 v137, v152, v153
	global_store_dwordx4 v[148:149], v[134:137], off offset:256 sc1
	v_pk_mul_f32 v[152:153], v[20:21], v[140:141] op_sel_hi:[1,0]
	v_pk_mul_f32 v[156:157], v[18:19], v[140:141] op_sel_hi:[1,0]
	v_add_u32_e32 v134, 0xa0, v130
	v_ashrrev_i32_e32 v135, 31, v134
	v_lshlrev_b64 v[148:149], 11, v[134:135]
	v_pk_mul_f32 v[136:137], v[24:25], v[140:141] op_sel_hi:[1,0]
	v_pk_mul_f32 v[134:135], v[22:23], v[140:141] op_sel_hi:[1,0]
	v_lshl_add_u64 v[148:149], s[8:9], 0, v[148:149]
	v_cvt_pk_bf16_f32 v134, v134, v135
	v_cvt_pk_bf16_f32 v135, v136, v137
	v_cvt_pk_bf16_f32 v136, v156, v157
	v_cvt_pk_bf16_f32 v137, v152, v153
	v_lshl_add_u64 v[148:149], v[148:149], 0, v[132:133]
	v_add_u32_e32 v130, 0xb0, v130
	global_store_dwordx4 v[148:149], v[134:137], off sc1
	v_ashrrev_i32_e32 v131, 31, v130
	v_pk_mul_f32 v[152:153], v[28:29], v[140:141] op_sel_hi:[1,0]
	v_pk_mul_f32 v[136:137], v[32:33], v[140:141] op_sel_hi:[1,0]
	v_pk_mul_f32 v[134:135], v[30:31], v[140:141] op_sel_hi:[1,0]
	v_pk_mul_f32 v[156:157], v[26:27], v[140:141] op_sel_hi:[1,0]
	v_cvt_pk_bf16_f32 v134, v134, v135
	v_cvt_pk_bf16_f32 v135, v136, v137
	v_lshlrev_b64 v[130:131], 11, v[130:131]
	v_cvt_pk_bf16_f32 v136, v156, v157
	v_cvt_pk_bf16_f32 v137, v152, v153
	global_store_dwordx4 v[148:149], v[134:137], off offset:256 sc1
	v_pk_mul_f32 v[148:149], v[4:5], v[138:139] op_sel_hi:[1,0]
	v_lshl_add_u64 v[130:131], s[8:9], 0, v[130:131]
	v_pk_mul_f32 v[136:137], v[8:9], v[138:139] op_sel_hi:[1,0]
	v_pk_mul_f32 v[134:135], v[6:7], v[138:139] op_sel_hi:[1,0]
	v_pk_mul_f32 v[152:153], v[2:3], v[138:139] op_sel_hi:[1,0]
	v_cvt_pk_bf16_f32 v134, v134, v135
	v_cvt_pk_bf16_f32 v135, v136, v137
	s_nop 0
	v_cvt_pk_bf16_f32 v136, v152, v153
	v_cvt_pk_bf16_f32 v137, v148, v149
	v_lshl_add_u64 v[148:149], v[130:131], 0, v[132:133]
	v_pk_mul_f32 v[132:133], v[16:17], v[138:139] op_sel_hi:[1,0]
	v_pk_mul_f32 v[130:131], v[14:15], v[138:139] op_sel_hi:[1,0]
	global_store_dwordx4 v[148:149], v[134:137], off sc1
	v_cvt_pk_bf16_f32 v130, v130, v131
	v_cvt_pk_bf16_f32 v131, v132, v133
	s_nop 1
	v_pk_mul_f32 v[134:135], v[12:13], v[138:139] op_sel_hi:[1,0]
	v_pk_mul_f32 v[136:137], v[10:11], v[138:139] op_sel_hi:[1,0]
	s_nop 0
	v_cvt_pk_bf16_f32 v132, v136, v137
	v_cvt_pk_bf16_f32 v133, v134, v135
	global_store_dwordx4 v[148:149], v[130:133], off offset:256 sc1
.LBB0_767:
	s_andn2_b64 vcc, exec, s[46:47]
	s_cbranch_vccnz .LBB0_769
	s_lshl_b32 s2, s24, 8
	s_add_i32 s2, s2, s16
	v_add_u32_e32 v130, s2, v183
	s_lshl_b32 s2, s40, 7
	s_or_b32 s2, s2, s83
	v_mul_f32_e32 v134, v158, v158
	v_pk_mul_f32 v[118:119], v[118:119], v[126:127]
	v_pk_mul_f32 v[114:115], v[114:115], v[122:123]
	v_lshl_add_u32 v132, v182, 3, s2
	v_pk_mul_f32 v[120:121], v[120:121], v[128:129]
	v_pk_mul_f32 v[118:119], v[118:119], v[134:135] op_sel_hi:[1,0]
	v_pk_mul_f32 v[116:117], v[116:117], v[124:125]
	v_pk_mul_f32 v[114:115], v[114:115], v[134:135] op_sel_hi:[1,0]
	v_ashrrev_i32_e32 v131, 31, v130
	v_readlane_b32 s12, v255, 0
	v_ashrrev_i32_e32 v133, 31, v132
	v_pk_mul_f32 v[120:121], v[120:121], v[134:135] op_sel_hi:[1,0]
	v_pk_mul_f32 v[122:123], v[116:117], v[134:135] op_sel_hi:[1,0]
	v_cvt_pk_bf16_f32 v116, v118, v119
	v_cvt_pk_bf16_f32 v117, v120, v121
	v_cvt_pk_bf16_f32 v118, v114, v115
	v_lshlrev_b64 v[114:115], 11, v[130:131]
	v_readlane_b32 s13, v255, 1
	v_cvt_pk_bf16_f32 v119, v122, v123
	v_pk_mul_f32 v[102:103], v[102:103], v[110:111]
	v_pk_mul_f32 v[100:101], v[100:101], v[108:109]
	v_lshl_add_u64 v[120:121], s[12:13], 0, v[114:115]
	v_lshlrev_b64 v[114:115], 1, v[132:133]
	v_lshl_add_u64 v[120:121], v[120:121], 0, v[114:115]
	global_store_dwordx4 v[120:121], v[116:119], off sc1
	v_pk_mul_f32 v[98:99], v[98:99], v[106:107]
	v_pk_mul_f32 v[104:105], v[104:105], v[112:113]
	v_add_u32_e32 v116, 16, v130
	v_mul_f32_e32 v118, v154, v154
	v_pk_mul_f32 v[102:103], v[102:103], v[118:119] op_sel_hi:[1,0]
	v_ashrrev_i32_e32 v117, 31, v116
	v_pk_mul_f32 v[106:107], v[100:101], v[118:119] op_sel_hi:[1,0]
	v_pk_mul_f32 v[100:101], v[98:99], v[118:119] op_sel_hi:[1,0]
	v_cvt_pk_bf16_f32 v98, v102, v103
	v_lshlrev_b64 v[102:103], 11, v[116:117]
	v_lshl_add_u64 v[102:103], s[12:13], 0, v[102:103]
	v_pk_mul_f32 v[104:105], v[104:105], v[118:119] op_sel_hi:[1,0]
	v_lshl_add_u64 v[102:103], v[102:103], 0, v[114:115]
	v_cvt_pk_bf16_f32 v99, v104, v105
	v_cvt_pk_bf16_f32 v100, v100, v101
	v_cvt_pk_bf16_f32 v101, v106, v107
	global_store_dwordx4 v[102:103], v[98:101], off sc1
	v_pk_mul_f32 v[86:87], v[86:87], v[94:95]
	v_pk_mul_f32 v[80:81], v[80:81], v[92:93]
	v_add_u32_e32 v98, 32, v130
	v_mul_f32_e32 v100, v150, v150
	v_pk_mul_f32 v[86:87], v[86:87], v[100:101] op_sel_hi:[1,0]
	v_pk_mul_f32 v[78:79], v[78:79], v[90:91]
	v_ashrrev_i32_e32 v99, 31, v98
	v_pk_mul_f32 v[90:91], v[80:81], v[100:101] op_sel_hi:[1,0]
	v_pk_mul_f32 v[80:81], v[78:79], v[100:101] op_sel_hi:[1,0]
	v_cvt_pk_bf16_f32 v78, v86, v87
	v_lshlrev_b64 v[86:87], 11, v[98:99]
	v_pk_mul_f32 v[88:89], v[88:89], v[96:97]
	v_lshl_add_u64 v[86:87], s[12:13], 0, v[86:87]
	v_pk_mul_f32 v[88:89], v[88:89], v[100:101] op_sel_hi:[1,0]
	v_lshl_add_u64 v[86:87], v[86:87], 0, v[114:115]
	v_cvt_pk_bf16_f32 v79, v88, v89
	v_cvt_pk_bf16_f32 v80, v80, v81
	v_cvt_pk_bf16_f32 v81, v90, v91
	global_store_dwordx4 v[86:87], v[78:81], off sc1
	v_pk_mul_f32 v[54:55], v[54:55], v[66:67]
	v_pk_mul_f32 v[48:49], v[48:49], v[60:61]
	v_add_u32_e32 v78, 48, v130
	v_mul_f32_e32 v80, v146, v146
	v_pk_mul_f32 v[54:55], v[54:55], v[80:81] op_sel_hi:[1,0]
	v_pk_mul_f32 v[46:47], v[46:47], v[58:59]
	v_ashrrev_i32_e32 v79, 31, v78
	v_pk_mul_f32 v[58:59], v[48:49], v[80:81] op_sel_hi:[1,0]
	v_pk_mul_f32 v[48:49], v[46:47], v[80:81] op_sel_hi:[1,0]
	v_cvt_pk_bf16_f32 v46, v54, v55
	v_lshlrev_b64 v[54:55], 11, v[78:79]
	v_lshl_add_u64 v[54:55], s[12:13], 0, v[54:55]
	v_pk_mul_f32 v[56:57], v[56:57], v[68:69]
	v_lshl_add_u64 v[54:55], v[54:55], 0, v[114:115]
	v_pk_mul_f32 v[56:57], v[56:57], v[80:81] op_sel_hi:[1,0]
	v_pk_mul_f32 v[60:61], v[62:63], v[74:75]
	v_cvt_pk_bf16_f32 v47, v56, v57
	v_cvt_pk_bf16_f32 v48, v48, v49
	v_cvt_pk_bf16_f32 v49, v58, v59
	global_store_dwordx4 v[54:55], v[46:49], off sc1
	v_add_u32_e32 v54, 0x80, v130
	v_ashrrev_i32_e32 v55, 31, v54
	v_mul_f32_e32 v46, v144, v144
	v_pk_mul_f32 v[48:49], v[72:73], v[84:85]
	v_lshlrev_b64 v[54:55], 11, v[54:55]
	v_pk_mul_f32 v[56:57], v[70:71], v[82:83]
	v_pk_mul_f32 v[48:49], v[48:49], v[46:47] op_sel_hi:[1,0]
	v_pk_mul_f32 v[58:59], v[64:65], v[76:77]
	v_lshl_add_u64 v[54:55], s[12:13], 0, v[54:55]
	v_pk_mul_f32 v[56:57], v[56:57], v[46:47] op_sel_hi:[1,0]
	v_pk_mul_f32 v[58:59], v[58:59], v[46:47] op_sel_hi:[1,0]
	v_pk_mul_f32 v[60:61], v[60:61], v[46:47] op_sel_hi:[1,0]
	v_cvt_pk_bf16_f32 v46, v56, v57
	v_cvt_pk_bf16_f32 v47, v48, v49
	v_lshl_add_u64 v[54:55], v[54:55], 0, v[114:115]
	v_cvt_pk_bf16_f32 v48, v60, v61
	v_cvt_pk_bf16_f32 v49, v58, v59
	global_store_dwordx4 v[54:55], v[46:49], off sc1
	v_pk_mul_f32 v[38:39], v[38:39], v[50:51]
	v_pk_mul_f32 v[36:37], v[36:37], v[44:45]
	v_add_u32_e32 v46, 0x90, v130
	v_mul_f32_e32 v48, v142, v142
	v_pk_mul_f32 v[38:39], v[38:39], v[48:49] op_sel_hi:[1,0]
	v_pk_mul_f32 v[34:35], v[34:35], v[42:43]
	v_ashrrev_i32_e32 v47, 31, v46
	v_pk_mul_f32 v[42:43], v[36:37], v[48:49] op_sel_hi:[1,0]
	v_pk_mul_f32 v[36:37], v[34:35], v[48:49] op_sel_hi:[1,0]
	v_cvt_pk_bf16_f32 v34, v38, v39
	v_lshlrev_b64 v[38:39], 11, v[46:47]
	v_pk_mul_f32 v[40:41], v[40:41], v[52:53]
	v_lshl_add_u64 v[38:39], s[12:13], 0, v[38:39]
	v_pk_mul_f32 v[40:41], v[40:41], v[48:49] op_sel_hi:[1,0]
	v_lshl_add_u64 v[38:39], v[38:39], 0, v[114:115]
	v_cvt_pk_bf16_f32 v35, v40, v41
	v_cvt_pk_bf16_f32 v36, v36, v37
	v_cvt_pk_bf16_f32 v37, v42, v43
	global_store_dwordx4 v[38:39], v[34:37], off sc1
	v_pk_mul_f32 v[22:23], v[22:23], v[30:31]
	v_pk_mul_f32 v[20:21], v[20:21], v[28:29]
	v_add_u32_e32 v34, 0xa0, v130
	v_mul_f32_e32 v36, v140, v140
	v_pk_mul_f32 v[22:23], v[22:23], v[36:37] op_sel_hi:[1,0]
	v_pk_mul_f32 v[18:19], v[18:19], v[26:27]
	v_ashrrev_i32_e32 v35, 31, v34
	v_pk_mul_f32 v[26:27], v[20:21], v[36:37] op_sel_hi:[1,0]
	v_pk_mul_f32 v[20:21], v[18:19], v[36:37] op_sel_hi:[1,0]
	v_cvt_pk_bf16_f32 v18, v22, v23
	v_lshlrev_b64 v[22:23], 11, v[34:35]
	v_pk_mul_f32 v[24:25], v[24:25], v[32:33]
	v_lshl_add_u64 v[22:23], s[12:13], 0, v[22:23]
	v_pk_mul_f32 v[24:25], v[24:25], v[36:37] op_sel_hi:[1,0]
	v_lshl_add_u64 v[22:23], v[22:23], 0, v[114:115]
	v_cvt_pk_bf16_f32 v19, v24, v25
	v_cvt_pk_bf16_f32 v20, v20, v21
	v_cvt_pk_bf16_f32 v21, v26, v27
	global_store_dwordx4 v[22:23], v[18:21], off sc1
	v_pk_mul_f32 v[6:7], v[6:7], v[14:15]
	v_pk_mul_f32 v[4:5], v[4:5], v[12:13]
	v_add_u32_e32 v18, 0xb0, v130
	v_mul_f32_e32 v20, v138, v138
	v_pk_mul_f32 v[6:7], v[6:7], v[20:21] op_sel_hi:[1,0]
	v_pk_mul_f32 v[2:3], v[2:3], v[10:11]
	v_ashrrev_i32_e32 v19, 31, v18
	v_pk_mul_f32 v[10:11], v[4:5], v[20:21] op_sel_hi:[1,0]
	v_pk_mul_f32 v[4:5], v[2:3], v[20:21] op_sel_hi:[1,0]
	v_cvt_pk_bf16_f32 v2, v6, v7
	v_lshlrev_b64 v[6:7], 11, v[18:19]
	v_lshl_add_u64 v[6:7], s[12:13], 0, v[6:7]
	v_pk_mul_f32 v[8:9], v[8:9], v[16:17]
	v_lshl_add_u64 v[6:7], v[6:7], 0, v[114:115]
	v_pk_mul_f32 v[8:9], v[8:9], v[20:21] op_sel_hi:[1,0]
	s_nop 0
	v_cvt_pk_bf16_f32 v3, v8, v9
	v_cvt_pk_bf16_f32 v4, v4, v5
	v_cvt_pk_bf16_f32 v5, v10, v11
	global_store_dwordx4 v[6:7], v[2:5], off sc1
